# bgemm branch loop: the one-at-a-time A-fragment reads of K tiles 1-3 get registers of their own (phase-unused constants, rebuilt at phase exit) and are issued with the tile's first reads; counted lgkm
# baseline (speedup 1.0000x reference)
; #define BG_STAGE(kk_, slot_) do { const int _n = (kk_) >> 2, _kt = (kk_) & 3; const int _so = (slot_) * STG; \
;         const bf16_t* _a = outs + ((size_t)_n * M + (size_t)pm * 256) * 256 + _kt * 64; const bf16_t* _b = wbr + ((size_t)_n * 1024 + (size_t)pn * 128) * 256 + _kt * 64; \
;         BG_LD(_so, _a); BG_LD(_so + HTB, _a + 128 * 256); BG_LDX(_so + 2 * HTB, _b, voffB); } while (0)
; #define BG_WAIT(n) asm volatile("s_waitcnt vmcnt(" #n ")" ::: "memory")
; #define BG_BAR() do { __builtin_amdgcn_s_barrier(); asm volatile("" ::: "memory"); } while (0)
; __device__ __forceinline__ void bgemm_phase(LAS unsigned char* lds, const bf16_t* outs, const bf16_t* wbr, const bf16_t* zg, bf16_t* merged) {
;     ...
;             BG_WAIT(6); BG_BAR(); { const int s2 = slot >= 1 ? slot - 1 : 2; BG_STAGE(kk0 + 2, s2); } BG_COMPUTE(slot); slot = slot == 2 ? 0 : slot + 1;
;             BG_WAIT(6); BG_BAR(); { const int s2 = slot >= 1 ? slot - 1 : 2; BG_STAGE(kk0 + 3, s2); } BG_COMPUTE(slot); slot = slot == 2 ? 0 : slot + 1;
;             BG_WAIT(6); BG_BAR(); if (n < 3) { const int s2 = slot >= 1 ? slot - 1 : 2; BG_STAGE(kk0 + 4, s2); } BG_COMPUTE(slot); slot = slot == 2 ? 0 : slot + 1;
.LBB0_296:
	s_mul_i32 s17, s16, 0xc000
	s_add_i32 s22, s17, 0xffff4000
	s_cmp_gt_i32 s16, 0
	s_cselect_b32 s22, s22, 0x18000
	v_lshl_add_u64 v[4:5], v[198:199], 0, s[20:21]
	s_add_i32 s22, s30, s22
	s_waitcnt vmcnt(6)
	s_barrier
	v_lshl_add_u64 v[6:7], v[196:197], 0, s[20:21]
	v_lshl_add_u64 v[12:13], v[4:5], 0, s[48:49]
	s_mov_b32 m0, s22
	v_lshl_add_u64 v[14:15], v[6:7], 0, s[48:49]
	global_load_lds_dwordx4 v[12:13], off
	s_add_i32 m0, s22, 0x2000
	v_lshl_add_u64 v[16:17], v[4:5], 0, s[50:51]
	global_load_lds_dwordx4 v[14:15], off
	s_add_i32 m0, s22, 0x4000
	v_lshl_add_u64 v[8:9], s[26:27], 0, v[110:111]
	v_lshl_add_u64 v[18:19], v[6:7], 0, s[50:51]
	global_load_lds_dwordx4 v[16:17], off
	s_add_i32 m0, s22, 0x6000
	v_lshl_add_u64 v[20:21], v[8:9], 0, s[48:49]
	s_add_i32 s17, s17, 0
	global_load_lds_dwordx4 v[18:19], off
	s_add_i32 m0, s22, 0x8000
	v_add_u32_e32 v140, s17, v3
	v_add_u32_e32 v60, s17, v145
	global_load_lds_dwordx4 v[20:21], off
	s_add_i32 m0, s22, 0xa000
	s_add_i32 s17, s16, 1
	s_cmp_lg_u32 s16, 2
	s_cselect_b32 s16, s17, 0
	s_mul_i32 s17, s16, 0xc000
	v_lshl_add_u64 v[10:11], s[26:27], 0, v[108:109]
	s_add_i32 s22, s17, 0xffff4000
	v_lshl_add_u64 v[22:23], v[10:11], 0, s[48:49]
	s_cmp_gt_i32 s16, 0
	global_load_lds_dwordx4 v[22:23], off
	s_cselect_b32 s22, s22, 0x18000
	ds_read_b128 v[12:15], v60 offset:32768
	ds_read_b128 v[16:19], v140
	ds_read_b128 v[20:23], v140 offset:1024
	ds_read_b128 v[24:27], v60 offset:33792
	ds_read_b128 v[32:35], v60 offset:34816
	ds_read_b128 v[36:39], v60 offset:35840
	ds_read_b128 v[44:47], v60 offset:36864
	ds_read_b128 v[48:51], v60 offset:37888
	ds_read_b128 v[56:59], v60 offset:38912
	ds_read_b128 v[60:63], v60 offset:39936
	ds_read_b128 v[64:67], v140 offset:2048
	ds_read_b128 v[68:71], v140 offset:3072
	ds_read_b128 v[84:87], v140 offset:4096
	ds_read_b128 v[88:91], v140 offset:5120
	ds_read_b128 v[218:221], v140 offset:6144
	ds_read_b128 v[222:225], v140 offset:7168
	s_add_i32 s22, s30, s22
	v_lshl_add_u64 v[140:141], v[4:5], 0, s[52:53]
	s_waitcnt vmcnt(6)
	s_barrier
	s_mov_b32 m0, s22
	v_lshl_add_u64 v[142:143], v[6:7], 0, s[52:53]
	global_load_lds_dwordx4 v[140:141], off
	s_add_i32 m0, s22, 0x2000
	v_lshl_add_u64 v[200:201], v[4:5], 0, s[54:55]
	global_load_lds_dwordx4 v[142:143], off
	s_add_i32 m0, s22, 0x4000
	s_waitcnt lgkmcnt(0)
	v_mfma_f32_16x16x32_bf16 v[28:31], v[12:15], v[16:19], 0
	global_load_lds_dwordx4 v[200:201], off
	s_add_i32 m0, s22, 0x6000
	v_mfma_f32_16x16x32_bf16 v[40:43], v[32:35], v[16:19], 0
	v_lshl_add_u64 v[226:227], v[10:11], 0, s[52:53]
	s_add_i32 s17, s17, 0
	v_add_u32_e32 v228, s17, v145
	v_mfma_f32_16x16x32_bf16 v[52:55], v[44:47], v[16:19], 0
	v_add_u32_e32 v217, s17, v3
	s_add_i32 s17, s16, 1
	v_mov_b64_e32 v[200:201], v[194:195]
	v_mfma_f32_16x16x32_bf16 v[16:19], v[56:59], v[16:19], 0
	s_mov_b64 s[28:29], 0x1000000
	v_lshl_add_u64 v[194:195], v[194:195], 0, s[28:29]
	v_mfma_f32_16x16x32_bf16 v[72:75], v[12:15], v[64:67], 0
	v_mfma_f32_16x16x32_bf16 v[76:79], v[32:35], v[64:67], 0
	v_mfma_f32_16x16x32_bf16 v[80:83], v[44:47], v[64:67], 0
	v_mfma_f32_16x16x32_bf16 v[64:67], v[56:59], v[64:67], 0
	v_mfma_f32_16x16x32_bf16 v[92:95], v[12:15], v[84:87], 0
	v_mfma_f32_16x16x32_bf16 v[96:99], v[32:35], v[84:87], 0
	v_mfma_f32_16x16x32_bf16 v[132:135], v[44:47], v[84:87], 0
	v_mfma_f32_16x16x32_bf16 v[84:87], v[56:59], v[84:87], 0
	v_mfma_f32_16x16x32_bf16 v[12:15], v[12:15], v[218:221], 0
	v_mfma_f32_16x16x32_bf16 v[32:35], v[32:35], v[218:221], 0
	v_mfma_f32_16x16x32_bf16 v[44:47], v[44:47], v[218:221], 0
	v_mfma_f32_16x16x32_bf16 v[56:59], v[56:59], v[218:221], 0
	v_lshl_add_u64 v[218:219], v[6:7], 0, s[54:55]
	v_lshl_add_u64 v[220:221], v[8:9], 0, s[52:53]
	global_load_lds_dwordx4 v[218:219], off
	s_add_i32 m0, s22, 0x8000
	v_mfma_f32_16x16x32_bf16 v[28:31], v[24:27], v[20:23], v[28:31]
	global_load_lds_dwordx4 v[220:221], off
	s_add_i32 m0, s22, 0xa000
	v_mfma_f32_16x16x32_bf16 v[40:43], v[36:39], v[20:23], v[40:43]
	global_load_lds_dwordx4 v[226:227], off
	s_cmp_lg_u32 s16, 2
	v_mfma_f32_16x16x32_bf16 v[52:55], v[48:51], v[20:23], v[52:55]
	s_cselect_b32 s16, s17, 0
	s_mul_i32 s17, s16, 0xc000
	s_add_i32 s22, s17, 0xffff4000
	v_mfma_f32_16x16x32_bf16 v[16:19], v[60:63], v[20:23], v[16:19]
	s_cmp_gt_i32 s16, 0
	s_cselect_b32 s22, s22, 0x18000
	s_add_i32 s22, s30, s22
	v_mfma_f32_16x16x32_bf16 v[20:23], v[24:27], v[68:71], v[72:75]
	s_mov_b32 m0, s22
	s_add_i32 s17, s17, 0
	v_add_u32_e32 v141, s17, v145
	v_mfma_f32_16x16x32_bf16 v[72:75], v[36:39], v[68:71], v[76:79]
	v_add_u32_e32 v140, s17, v3
	s_add_i32 s17, s16, 1
	v_mfma_f32_16x16x32_bf16 v[76:79], v[48:51], v[68:71], v[80:83]
	v_mfma_f32_16x16x32_bf16 v[64:67], v[60:63], v[68:71], v[64:67]
	v_mfma_f32_16x16x32_bf16 v[68:71], v[24:27], v[88:91], v[92:95]
	v_mfma_f32_16x16x32_bf16 v[80:83], v[36:39], v[88:91], v[96:99]
	v_mfma_f32_16x16x32_bf16 v[12:15], v[24:27], v[222:225], v[12:15]
	v_mfma_f32_16x16x32_bf16 v[24:27], v[36:39], v[222:225], v[32:35]
	ds_read_b128 v[36:39], v228 offset:32768
	v_mfma_f32_16x16x32_bf16 v[92:95], v[48:51], v[88:91], v[132:135]
	v_mfma_f32_16x16x32_bf16 v[84:87], v[60:63], v[88:91], v[84:87]
	v_mfma_f32_16x16x32_bf16 v[32:35], v[48:51], v[222:225], v[44:47]
	v_mfma_f32_16x16x32_bf16 v[44:47], v[60:63], v[222:225], v[56:59]
	ds_read_b128 v[48:51], v217
	s_nop 1
	ds_read_b128 v[56:59], v217 offset:1024
	ds_read_b128 v[60:63], v228 offset:33792
	ds_read_b128 v[88:91], v228 offset:34816
	ds_read_b128 v[96:99], v228 offset:35840
	ds_read_b128 v[132:135], v228 offset:36864
	ds_read_b128 v[218:221], v228 offset:37888
	ds_read_b128 v[222:225], v228 offset:38912
	ds_read_b128 v[226:229], v228 offset:39936
	ds_read_b128 v[136:139], v217 offset:2048
	ds_read_b128 v[204:207], v217 offset:4096
	ds_read_b128 v[208:211], v217 offset:6144
	s_waitcnt lgkmcnt(3)
	v_mfma_f32_16x16x32_bf16 v[28:31], v[36:39], v[48:51], v[28:31]
	v_mfma_f32_16x16x32_bf16 v[40:43], v[88:91], v[48:51], v[40:43]
	v_mfma_f32_16x16x32_bf16 v[52:55], v[132:135], v[48:51], v[52:55]
	v_mfma_f32_16x16x32_bf16 v[16:19], v[222:225], v[48:51], v[16:19]
	ds_read_b128 v[230:233], v217 offset:3072
	s_waitcnt lgkmcnt(3)
	v_mfma_f32_16x16x32_bf16 v[20:23], v[36:39], v[136:139], v[20:23]
	v_mfma_f32_16x16x32_bf16 v[72:75], v[88:91], v[136:139], v[72:75]
	v_mfma_f32_16x16x32_bf16 v[76:79], v[132:135], v[136:139], v[76:79]
	v_mfma_f32_16x16x32_bf16 v[48:51], v[222:225], v[136:139], v[64:67]
	s_nop 2
	ds_read_b128 v[234:237], v217 offset:5120
	s_waitcnt lgkmcnt(3)
	v_mfma_f32_16x16x32_bf16 v[68:71], v[36:39], v[204:207], v[68:71]
	v_mfma_f32_16x16x32_bf16 v[80:83], v[88:91], v[204:207], v[80:83]
	v_mfma_f32_16x16x32_bf16 v[92:95], v[132:135], v[204:207], v[92:95]
	v_mfma_f32_16x16x32_bf16 v[64:67], v[222:225], v[204:207], v[84:87]
	s_nop 2
	ds_read_b128 v[238:241], v217 offset:7168
	s_waitcnt vmcnt(6)
	s_barrier
; #define BG_STAGE(kk_, slot_) do { const int _n = (kk_) >> 2, _kt = (kk_) & 3; const int _so = (slot_) * STG; \
;         const bf16_t* _a = outs + ((size_t)_n * M + (size_t)pm * 256) * 256 + _kt * 64; const bf16_t* _b = wbr + ((size_t)_n * 1024 + (size_t)pn * 128) * 256 + _kt * 64; \
;         BG_LD(_so, _a); BG_LD(_so + HTB, _a + 128 * 256); BG_LDX(_so + 2 * HTB, _b, voffB); } while (0)
; #define BG_WAIT(n) asm volatile("s_waitcnt vmcnt(" #n ")" ::: "memory")
; #define BG_BAR() do { __builtin_amdgcn_s_barrier(); asm volatile("" ::: "memory"); } while (0)
; __device__ __forceinline__ void bgemm_phase(LAS unsigned char* lds, const bf16_t* outs, const bf16_t* wbr, const bf16_t* zg, bf16_t* merged) {
;     ...
;             BG_WAIT(6); BG_BAR(); { const int s2 = slot >= 1 ? slot - 1 : 2; BG_STAGE(kk0 + 2, s2); } BG_COMPUTE(slot); slot = slot == 2 ? 0 : slot + 1;
;             BG_WAIT(6); BG_BAR(); { const int s2 = slot >= 1 ? slot - 1 : 2; BG_STAGE(kk0 + 3, s2); } BG_COMPUTE(slot); slot = slot == 2 ? 0 : slot + 1;
;             BG_WAIT(6); BG_BAR(); if (n < 3) { const int s2 = slot >= 1 ? slot - 1 : 2; BG_STAGE(kk0 + 4, s2); } BG_COMPUTE(slot); slot = slot == 2 ? 0 : slot + 1;
;             if (n < 3) { BG_WAIT(6); } else { BG_WAIT(0); }
;             BG_BAR(); if (n < 3) { const int s2 = slot >= 1 ? slot - 1 : 2; BG_STAGE(kk0 + 5, s2); }
;             size_t goff = (((size_t)n * 64 + pm) * 8 + pn) * 32768 + (size_t)(((wm * 4) * 4 + wn * 2) * 64 + fq * 16 + fr) * 8;
;             asm volatile("" : "+v"(goff) :: "memory");
;             const bf16_t* gp0 = zg + goff;
;             u32x4 gv[2][2];
; #pragma unroll
;             for (int mi = 0; mi < 2; ++mi)
; #pragma unroll
;                 for (int g = 0; g < 2; ++g) gv[mi][g] = *(const u32x4*)(gp0 + (mi * 4 + g) * 512);
;             BG_COMPUTE(slot); slot = slot == 2 ? 0 : slot + 1;
	s_waitcnt lgkmcnt(3)
	v_mfma_f32_16x16x32_bf16 v[12:15], v[36:39], v[208:211], v[12:15]
	v_mfma_f32_16x16x32_bf16 v[24:27], v[88:91], v[208:211], v[24:27]
	v_lshl_add_u64 v[88:89], v[4:5], 0, s[58:59]
	v_lshl_add_u64 v[90:91], v[6:7], 0, s[58:59]
	v_mfma_f32_16x16x32_bf16 v[32:35], v[132:135], v[208:211], v[32:35]
	v_lshl_add_u64 v[132:133], v[8:9], 0, s[60:61]
	v_lshl_add_u64 v[134:135], v[10:11], 0, s[60:61]
	v_lshl_add_u64 v[8:9], v[8:9], 0, s[66:67]
	v_mfma_f32_16x16x32_bf16 v[36:39], v[222:225], v[208:211], v[44:47]
	s_waitcnt lgkmcnt(0)
	v_lshl_add_u64 v[84:85], v[4:5], 0, s[56:57]
	v_lshl_add_u64 v[86:87], v[6:7], 0, s[56:57]
	global_load_lds_dwordx4 v[84:85], off
	s_add_i32 m0, s22, 0x2000
	v_mfma_f32_16x16x32_bf16 v[28:31], v[60:63], v[56:59], v[28:31]
	global_load_lds_dwordx4 v[86:87], off
	s_add_i32 m0, s22, 0x4000
	v_mfma_f32_16x16x32_bf16 v[20:23], v[60:63], v[230:233], v[20:23]
	global_load_lds_dwordx4 v[88:89], off
	s_add_i32 m0, s22, 0x6000
	v_mfma_f32_16x16x32_bf16 v[68:71], v[60:63], v[234:237], v[68:71]
	global_load_lds_dwordx4 v[90:91], off
	s_add_i32 m0, s22, 0x8000
	v_mfma_f32_16x16x32_bf16 v[12:15], v[60:63], v[238:241], v[12:15]
	global_load_lds_dwordx4 v[132:133], off
	s_add_i32 m0, s22, 0xa000
	v_mfma_f32_16x16x32_bf16 v[40:43], v[96:99], v[56:59], v[40:43]
	global_load_lds_dwordx4 v[134:135], off
	ds_read_b128 v[60:63], v141 offset:32768
	v_mfma_f32_16x16x32_bf16 v[44:47], v[218:221], v[56:59], v[52:55]
	s_cmp_lg_u32 s16, 2
	s_cselect_b32 s16, s17, 0
	s_mul_i32 s17, s16, 0xc000
	v_mfma_f32_16x16x32_bf16 v[16:19], v[226:229], v[56:59], v[16:19]
	s_add_i32 s22, s17, 0xffff4000
	s_cmp_gt_i32 s16, 0
	s_cselect_b32 s22, s22, 0x18000
	v_mfma_f32_16x16x32_bf16 v[52:55], v[96:99], v[230:233], v[72:75]
	s_add_i32 s22, s30, s22
	s_mov_b32 m0, s22
	v_lshl_add_u64 v[10:11], v[10:11], 0, s[66:67]
	v_mfma_f32_16x16x32_bf16 v[56:59], v[218:221], v[230:233], v[76:79]
	s_add_i32 s17, s17, 0
	v_add_u32_e32 v217, s17, v3
	v_mfma_f32_16x16x32_bf16 v[48:51], v[226:229], v[230:233], v[48:51]
	v_mfma_f32_16x16x32_bf16 v[72:75], v[96:99], v[234:237], v[80:83]
	s_nop 2
	ds_read_b128 v[80:83], v140
	ds_read_b128 v[84:87], v140 offset:1024
	ds_read_b128 v[88:91], v141 offset:33792
	v_mfma_f32_16x16x32_bf16 v[76:79], v[218:221], v[234:237], v[92:95]
	v_mfma_f32_16x16x32_bf16 v[64:67], v[226:229], v[234:237], v[64:67]
	v_mfma_f32_16x16x32_bf16 v[24:27], v[96:99], v[238:241], v[24:27]
	s_nop 0
	ds_read_b128 v[92:95], v141 offset:34816
	ds_read_b128 v[96:99], v141 offset:35840
	v_mfma_f32_16x16x32_bf16 v[32:35], v[218:221], v[238:241], v[32:35]
	ds_read_b128 v[132:135], v141 offset:36864
	ds_read_b128 v[218:221], v141 offset:37888
	v_mfma_f32_16x16x32_bf16 v[36:39], v[226:229], v[238:241], v[36:39]
	ds_read_b128 v[222:225], v141 offset:38912
	ds_read_b128 v[226:229], v141 offset:39936
	ds_read_b128 v[136:139], v140 offset:2048
	ds_read_b128 v[204:207], v140 offset:4096
	ds_read_b128 v[208:211], v140 offset:6144
	s_waitcnt lgkmcnt(3)
	v_mfma_f32_16x16x32_bf16 v[28:31], v[60:63], v[80:83], v[28:31]
	v_mfma_f32_16x16x32_bf16 v[40:43], v[92:95], v[80:83], v[40:43]
	v_mfma_f32_16x16x32_bf16 v[44:47], v[132:135], v[80:83], v[44:47]
	v_mfma_f32_16x16x32_bf16 v[16:19], v[222:225], v[80:83], v[16:19]
	ds_read_b128 v[230:233], v140 offset:3072
	s_waitcnt lgkmcnt(3)
	v_mfma_f32_16x16x32_bf16 v[20:23], v[60:63], v[136:139], v[20:23]
	v_mfma_f32_16x16x32_bf16 v[52:55], v[92:95], v[136:139], v[52:55]
	v_mfma_f32_16x16x32_bf16 v[56:59], v[132:135], v[136:139], v[56:59]
	v_mfma_f32_16x16x32_bf16 v[48:51], v[222:225], v[136:139], v[48:51]
	ds_read_b128 v[234:237], v140 offset:5120
	s_waitcnt lgkmcnt(3)
	v_mfma_f32_16x16x32_bf16 v[68:71], v[60:63], v[204:207], v[68:71]
	v_mfma_f32_16x16x32_bf16 v[72:75], v[92:95], v[204:207], v[72:75]
	v_mfma_f32_16x16x32_bf16 v[76:79], v[132:135], v[204:207], v[76:79]
	v_mfma_f32_16x16x32_bf16 v[64:67], v[222:225], v[204:207], v[64:67]
	ds_read_b128 v[238:241], v140 offset:7168
	s_waitcnt vmcnt(6)
	s_barrier
	s_waitcnt lgkmcnt(3)
	v_mfma_f32_16x16x32_bf16 v[12:15], v[60:63], v[208:211], v[12:15]
	v_mfma_f32_16x16x32_bf16 v[24:27], v[92:95], v[208:211], v[24:27]
	v_mfma_f32_16x16x32_bf16 v[32:35], v[132:135], v[208:211], v[32:35]
	v_mfma_f32_16x16x32_bf16 v[36:39], v[222:225], v[208:211], v[36:39]
	s_waitcnt lgkmcnt(0)
	v_lshl_add_u64 v[80:81], v[4:5], 0, s[62:63]
	v_lshl_add_u64 v[82:83], v[6:7], 0, s[62:63]
	global_load_lds_dwordx4 v[80:81], off
	s_add_i32 m0, s22, 0x2000
	v_mfma_f32_16x16x32_bf16 v[60:63], v[226:229], v[84:87], v[16:19]
	global_load_lds_dwordx4 v[82:83], off
	s_add_i32 m0, s22, 0x4000
	s_nop 0
	v_lshl_add_u64 v[16:17], v[4:5], 0, s[64:65]
	v_lshl_add_u64 v[18:19], v[6:7], 0, s[64:65]
	global_load_lds_dwordx4 v[16:17], off
	s_add_i32 m0, s22, 0x6000
	v_mfma_f32_16x16x32_bf16 v[28:31], v[88:91], v[84:87], v[28:31]
	global_load_lds_dwordx4 v[18:19], off
	s_add_i32 m0, s22, 0x8000
	v_mfma_f32_16x16x32_bf16 v[4:7], v[88:91], v[230:233], v[20:23]
	global_load_lds_dwordx4 v[8:9], off
	s_add_i32 m0, s22, 0xa000
	s_nop 0
	v_add_u32_e32 v20, s17, v145
	global_load_lds_dwordx4 v[10:11], off
	v_mfma_f32_16x16x32_bf16 v[44:47], v[218:221], v[84:87], v[44:47]
	s_add_i32 s17, s16, 1
	s_cmp_lg_u32 s16, 2
	s_cselect_b32 s16, s17, 0
	v_mfma_f32_16x16x32_bf16 v[52:55], v[96:99], v[230:233], v[52:55]
	s_add_u32 s20, s20, 0x800000
	s_addc_u32 s21, s21, 0
	s_add_u32 s26, s26, 0x80000
	v_mfma_f32_16x16x32_bf16 v[56:59], v[218:221], v[230:233], v[56:59]
	s_addc_u32 s27, s27, 0
	s_cmp_eq_u32 s20, 0x1800000
	v_mfma_f32_16x16x32_bf16 v[48:51], v[226:229], v[230:233], v[48:51]
	v_mfma_f32_16x16x32_bf16 v[222:225], v[218:221], v[234:237], v[76:79]
	v_mfma_f32_16x16x32_bf16 v[230:233], v[226:229], v[234:237], v[64:67]
	v_mfma_f32_16x16x32_bf16 v[242:245], v[96:99], v[238:241], v[24:27]
	v_mfma_f32_16x16x32_bf16 v[218:221], v[218:221], v[238:241], v[32:35]
	v_mfma_f32_16x16x32_bf16 v[36:39], v[226:229], v[238:241], v[36:39]
	ds_read_b128 v[226:229], v20 offset:32768
	s_nop 0
	ds_read_b128 v[32:35], v217
	ds_read_b128 v[24:27], v217 offset:1024
	ds_read_b128 v[8:11], v20 offset:33792
	v_mfma_f32_16x16x32_bf16 v[40:43], v[96:99], v[84:87], v[40:43]
	v_mfma_f32_16x16x32_bf16 v[68:71], v[88:91], v[234:237], v[68:71]
	v_mfma_f32_16x16x32_bf16 v[132:135], v[96:99], v[234:237], v[72:75]
	v_mfma_f32_16x16x32_bf16 v[234:237], v[88:91], v[238:241], v[12:15]
	ds_read_b128 v[246:249], v20 offset:34816
	s_nop 1
	ds_read_b128 v[12:15], v20 offset:35840
	ds_read_b128 v[250:253], v20 offset:36864
	ds_read_b128 v[16:19], v20 offset:37888
	ds_read_b128 v[140:143], v20 offset:38912
	ds_read_b128 v[20:23], v20 offset:39936
	ds_read_b128 v[136:139], v217 offset:2048
	ds_read_b128 v[204:207], v217 offset:4096
	ds_read_b128 v[208:211], v217 offset:6144
	s_waitcnt lgkmcnt(3)
; __device__ __forceinline__ float bflo(unsigned w) { return __uint_as_float(w << 16); }
; __device__ __forceinline__ float bfhi(unsigned w) { return __uint_as_float(w & 0xffff0000u); }
; __device__ __forceinline__ float sigm(float x) { return frcp(1.f + fexp(-x)); }
; __device__ __forceinline__ void bgemm_phase(LAS unsigned char* lds, const bf16_t* outs, const bf16_t* wbr, const bf16_t* zg, bf16_t* merged) {
;     ...
;                 for (int g = 0; g < 2; ++g) gv[mi][g] = *(const u32x4*)(gp0 + (mi * 4 + g) * 512);
;             BG_COMPUTE(slot); slot = slot == 2 ? 0 : slot + 1;
; #pragma unroll
;             for (int hf = 0; hf < 2; ++hf) {
;                 u32x4 gn[2][2];
;                 if (hf == 0) {
; #pragma unroll
;                     for (int mi = 0; mi < 2; ++mi)
; #pragma unroll
;                         for (int g = 0; g < 2; ++g) gn[mi][g] = *(const u32x4*)(gp0 + ((2 + mi) * 4 + g) * 512);
;                 }
; #pragma unroll
;                 for (int mi = 0; mi < 2; ++mi)
; #pragma unroll
;                     for (int g = 0; g < 2; ++g) { const u32x4 gq = gv[mi][g]; const int m2 = hf * 2 + mi;
;                         tot[m2][2 * g][0] += sigm(bflo(gq.x)) * acc[m2][2 * g][0]; tot[m2][2 * g][1] += sigm(bfhi(gq.x)) * acc[m2][2 * g][1];
;                         tot[m2][2 * g][2] += sigm(bflo(gq.y)) * acc[m2][2 * g][2]; tot[m2][2 * g][3] += sigm(bfhi(gq.y)) * acc[m2][2 * g][3];
;                         tot[m2][2 * g + 1][0] += sigm(bflo(gq.z)) * acc[m2][2 * g + 1][0]; tot[m2][2 * g + 1][1] += sigm(bfhi(gq.z)) * acc[m2][2 * g + 1][1];
;                         tot[m2][2 * g + 1][2] += sigm(bflo(gq.w)) * acc[m2][2 * g + 1][2]; tot[m2][2 * g + 1][3] += sigm(bfhi(gq.w)) * acc[m2][2 * g + 1][3];
;                         acc[m2][2 * g] = ZERO4; acc[m2][2 * g + 1] = ZERO4; }
	v_mfma_f32_16x16x32_bf16 v[238:241], v[226:229], v[32:35], v[28:31]
	s_nop 2
	ds_read_b128 v[64:67], v217 offset:3072
	v_mfma_f32_16x16x32_bf16 v[96:99], v[246:249], v[32:35], v[40:43]
	v_mfma_f32_16x16x32_bf16 v[92:95], v[250:253], v[32:35], v[44:47]
	v_mfma_f32_16x16x32_bf16 v[88:91], v[140:143], v[32:35], v[60:63]
	s_waitcnt lgkmcnt(3)
	v_mfma_f32_16x16x32_bf16 v[84:87], v[226:229], v[136:139], v[4:7]
	s_nop 2
	ds_read_b128 v[32:35], v217 offset:5120
	v_mfma_f32_16x16x32_bf16 v[80:83], v[246:249], v[136:139], v[52:55]
	v_mfma_f32_16x16x32_bf16 v[76:79], v[250:253], v[136:139], v[56:59]
	v_mfma_f32_16x16x32_bf16 v[72:75], v[140:143], v[136:139], v[48:51]
	s_waitcnt lgkmcnt(3)
	v_mfma_f32_16x16x32_bf16 v[68:71], v[226:229], v[204:207], v[68:71]
	v_mfma_f32_16x16x32_bf16 v[56:59], v[246:249], v[204:207], v[132:135]
	v_mfma_f32_16x16x32_bf16 v[48:51], v[250:253], v[204:207], v[222:225]
	v_mfma_f32_16x16x32_bf16 v[40:43], v[140:143], v[204:207], v[230:233]
	ds_read_b128 v[28:31], v217 offset:7168
	s_waitcnt lgkmcnt(3)
	v_mfma_f32_16x16x32_bf16 v[36:39], v[140:143], v[208:211], v[36:39]
	v_lshl_add_u64 v[140:141], v[200:201], 1, s[8:9]
	v_add_co_u32_e32 v142, vcc, s80, v140
	v_mfma_f32_16x16x32_bf16 v[60:63], v[226:229], v[208:211], v[234:237]
	s_nop 0
	v_addc_co_u32_e32 v143, vcc, 0, v141, vcc
	v_add_co_u32_e32 v200, vcc, s81, v140
	v_mfma_f32_16x16x32_bf16 v[52:55], v[246:249], v[208:211], v[242:245]
	s_nop 0
	v_addc_co_u32_e32 v201, vcc, 0, v141, vcc
	global_load_dwordx4 v[132:135], v[140:141], off offset:1024
	v_mfma_f32_16x16x32_bf16 v[44:47], v[250:253], v[208:211], v[218:221]
	s_waitcnt lgkmcnt(0)
	s_nop 2
	v_add_co_u32_e32 v218, vcc, s82, v140
	v_mfma_f32_16x16x32_bf16 v[4:7], v[8:11], v[24:27], v[238:241]
	s_nop 0
	v_addc_co_u32_e32 v219, vcc, 0, v141, vcc
	v_mfma_f32_16x16x32_bf16 v[96:99], v[12:15], v[24:27], v[96:99]
	v_mfma_f32_16x16x32_bf16 v[92:95], v[16:19], v[24:27], v[92:95]
	v_mfma_f32_16x16x32_bf16 v[24:27], v[20:23], v[24:27], v[88:91]
	v_mfma_f32_16x16x32_bf16 v[84:87], v[8:11], v[64:67], v[84:87]
	s_nop 1
	global_load_dwordx4 v[88:91], v[140:141], off
	s_nop 0
	global_load_dwordx4 v[140:143], v[142:143], off offset:1024
	v_mfma_f32_16x16x32_bf16 v[80:83], v[12:15], v[64:67], v[80:83]
	s_waitcnt vmcnt(0)
	v_lshlrev_b32_e32 v220, 16, v141
	v_mfma_f32_16x16x32_bf16 v[76:79], v[16:19], v[64:67], v[76:79]
	v_and_b32_e32 v141, 0xffff0000, v141
	v_lshlrev_b32_e32 v221, 16, v142
	v_and_b32_e32 v142, 0xffff0000, v142
	v_mfma_f32_16x16x32_bf16 v[64:67], v[20:23], v[64:67], v[72:75]
	v_lshlrev_b32_e32 v222, 16, v143
	v_and_b32_e32 v143, 0xffff0000, v143
	v_mul_f32_e32 v220, 0xbfb8aa3b, v220
	v_mfma_f32_16x16x32_bf16 v[68:71], v[8:11], v[32:35], v[68:71]
	global_load_dwordx4 v[72:75], v[200:201], off offset:-4096
	v_mul_f32_e32 v141, 0xbfb8aa3b, v141
	v_mul_f32_e32 v221, 0xbfb8aa3b, v221
	v_mfma_f32_16x16x32_bf16 v[56:59], v[12:15], v[32:35], v[56:59]
	v_mul_f32_e32 v142, 0xbfb8aa3b, v142
	v_mul_f32_e32 v222, 0xbfb8aa3b, v222
	v_mul_f32_e32 v143, 0xbfb8aa3b, v143
	v_mfma_f32_16x16x32_bf16 v[48:51], v[16:19], v[32:35], v[48:51]
	v_exp_f32_e32 v220, v220
	v_exp_f32_e32 v141, v141
	v_exp_f32_e32 v221, v221
	v_mfma_f32_16x16x32_bf16 v[32:35], v[20:23], v[32:35], v[40:43]
	v_exp_f32_e32 v142, v142
	v_exp_f32_e32 v222, v222
	v_exp_f32_e32 v143, v143
	global_load_dwordx4 v[40:43], v[200:201], off
	v_mfma_f32_16x16x32_bf16 v[8:11], v[8:11], v[28:31], v[60:63]
	v_add_f32_e32 v143, 1.0, v143
	s_waitcnt vmcnt(1)
	v_lshlrev_b32_e32 v217, 16, v74
	global_load_dwordx4 v[60:63], v[200:201], off offset:1024
	v_mfma_f32_16x16x32_bf16 v[12:15], v[12:15], v[28:31], v[52:55]
	v_lshlrev_b32_e32 v200, 16, v72
	v_and_b32_e32 v72, 0xffff0000, v72
	v_lshlrev_b32_e32 v201, 16, v73
	global_load_dwordx4 v[52:55], v[218:219], off
	v_mfma_f32_16x16x32_bf16 v[16:19], v[16:19], v[28:31], v[44:47]
	v_and_b32_e32 v73, 0xffff0000, v73
	v_and_b32_e32 v74, 0xffff0000, v74
	v_mul_f32_e32 v200, 0xbfb8aa3b, v200
	global_load_dwordx4 v[44:47], v[218:219], off offset:1024
	v_mfma_f32_16x16x32_bf16 v[20:23], v[20:23], v[28:31], v[36:39]
	v_lshlrev_b32_e32 v28, 16, v88
	v_and_b32_e32 v29, 0xffff0000, v88
	v_lshlrev_b32_e32 v30, 16, v89
	v_and_b32_e32 v31, 0xffff0000, v89
	v_lshlrev_b32_e32 v36, 16, v90
	v_and_b32_e32 v37, 0xffff0000, v90
	v_lshlrev_b32_e32 v38, 16, v91
	v_and_b32_e32 v39, 0xffff0000, v91
	v_lshlrev_b32_e32 v88, 16, v132
	v_and_b32_e32 v89, 0xffff0000, v132
	v_lshlrev_b32_e32 v90, 16, v133
	v_and_b32_e32 v91, 0xffff0000, v133
	v_lshlrev_b32_e32 v132, 16, v134
	v_and_b32_e32 v133, 0xffff0000, v134
	v_lshlrev_b32_e32 v134, 16, v135
	v_and_b32_e32 v135, 0xffff0000, v135
	v_lshlrev_b32_e32 v218, 16, v75
	v_and_b32_e32 v75, 0xffff0000, v75
	v_lshlrev_b32_e32 v219, 16, v140
	v_and_b32_e32 v140, 0xffff0000, v140
	s_waitcnt vmcnt(3)
	v_lshlrev_b32_e32 v223, 16, v40
	v_and_b32_e32 v40, 0xffff0000, v40
	v_lshlrev_b32_e32 v224, 16, v41
	v_and_b32_e32 v41, 0xffff0000, v41
	v_lshlrev_b32_e32 v225, 16, v42
	v_and_b32_e32 v42, 0xffff0000, v42
	v_lshlrev_b32_e32 v226, 16, v43
	v_and_b32_e32 v43, 0xffff0000, v43
	v_mul_f32_e32 v28, 0xbfb8aa3b, v28
	v_mul_f32_e32 v29, 0xbfb8aa3b, v29
	v_mul_f32_e32 v30, 0xbfb8aa3b, v30
	v_mul_f32_e32 v31, 0xbfb8aa3b, v31
	v_mul_f32_e32 v36, 0xbfb8aa3b, v36
	v_mul_f32_e32 v37, 0xbfb8aa3b, v37
	v_mul_f32_e32 v38, 0xbfb8aa3b, v38
	v_mul_f32_e32 v39, 0xbfb8aa3b, v39
	v_mul_f32_e32 v88, 0xbfb8aa3b, v88
	v_mul_f32_e32 v89, 0xbfb8aa3b, v89
	v_mul_f32_e32 v90, 0xbfb8aa3b, v90
	v_mul_f32_e32 v91, 0xbfb8aa3b, v91
	v_mul_f32_e32 v132, 0xbfb8aa3b, v132
	v_mul_f32_e32 v133, 0xbfb8aa3b, v133
	v_mul_f32_e32 v134, 0xbfb8aa3b, v134
	v_mul_f32_e32 v135, 0xbfb8aa3b, v135
	v_mul_f32_e32 v72, 0xbfb8aa3b, v72
	v_mul_f32_e32 v201, 0xbfb8aa3b, v201
	v_mul_f32_e32 v73, 0xbfb8aa3b, v73
	v_mul_f32_e32 v217, 0xbfb8aa3b, v217
	v_mul_f32_e32 v74, 0xbfb8aa3b, v74
	v_mul_f32_e32 v218, 0xbfb8aa3b, v218
	v_mul_f32_e32 v75, 0xbfb8aa3b, v75
	v_mul_f32_e32 v219, 0xbfb8aa3b, v219
	v_mul_f32_e32 v140, 0xbfb8aa3b, v140
	v_mul_f32_e32 v223, 0xbfb8aa3b, v223
	v_mul_f32_e32 v40, 0xbfb8aa3b, v40
	v_mul_f32_e32 v224, 0xbfb8aa3b, v224
	v_mul_f32_e32 v41, 0xbfb8aa3b, v41
	v_mul_f32_e32 v225, 0xbfb8aa3b, v225
	v_mul_f32_e32 v42, 0xbfb8aa3b, v42
	v_mul_f32_e32 v226, 0xbfb8aa3b, v226
	v_mul_f32_e32 v43, 0xbfb8aa3b, v43
	v_exp_f32_e32 v28, v28
	v_exp_f32_e32 v29, v29
	v_exp_f32_e32 v30, v30
	v_exp_f32_e32 v31, v31
	v_exp_f32_e32 v36, v36
	v_exp_f32_e32 v37, v37
	v_exp_f32_e32 v38, v38
	s_waitcnt vmcnt(2)
; __device__ __forceinline__ float bflo(unsigned w) { return __uint_as_float(w << 16); }
; __device__ __forceinline__ float bfhi(unsigned w) { return __uint_as_float(w & 0xffff0000u); }
; __device__ __forceinline__ float sigm(float x) { return frcp(1.f + fexp(-x)); }
; __device__ __forceinline__ void bgemm_phase(LAS unsigned char* lds, const bf16_t* outs, const bf16_t* wbr, const bf16_t* zg, bf16_t* merged) {
;     ...
;                     for (int g = 0; g < 2; ++g) { const u32x4 gq = gv[mi][g]; const int m2 = hf * 2 + mi;
;                         tot[m2][2 * g][0] += sigm(bflo(gq.x)) * acc[m2][2 * g][0]; tot[m2][2 * g][1] += sigm(bfhi(gq.x)) * acc[m2][2 * g][1];
;                         tot[m2][2 * g][2] += sigm(bflo(gq.y)) * acc[m2][2 * g][2]; tot[m2][2 * g][3] += sigm(bfhi(gq.y)) * acc[m2][2 * g][3];
;                         tot[m2][2 * g + 1][0] += sigm(bflo(gq.z)) * acc[m2][2 * g + 1][0]; tot[m2][2 * g + 1][1] += sigm(bfhi(gq.z)) * acc[m2][2 * g + 1][1];
;                         tot[m2][2 * g + 1][2] += sigm(bflo(gq.w)) * acc[m2][2 * g + 1][2]; tot[m2][2 * g + 1][3] += sigm(bfhi(gq.w)) * acc[m2][2 * g + 1][3];
;                         acc[m2][2 * g] = ZERO4; acc[m2][2 * g + 1] = ZERO4; }
	v_lshlrev_b32_e32 v227, 16, v60
	v_and_b32_e32 v60, 0xffff0000, v60
	v_lshlrev_b32_e32 v228, 16, v61
	v_and_b32_e32 v61, 0xffff0000, v61
	v_lshlrev_b32_e32 v229, 16, v62
	v_and_b32_e32 v62, 0xffff0000, v62
	v_lshlrev_b32_e32 v230, 16, v63
	v_and_b32_e32 v63, 0xffff0000, v63
	s_waitcnt vmcnt(1)
	v_lshlrev_b32_e32 v231, 16, v52
	v_and_b32_e32 v52, 0xffff0000, v52
	v_lshlrev_b32_e32 v232, 16, v53
	v_and_b32_e32 v53, 0xffff0000, v53
	v_lshlrev_b32_e32 v233, 16, v54
	v_and_b32_e32 v54, 0xffff0000, v54
	v_lshlrev_b32_e32 v234, 16, v55
	v_and_b32_e32 v55, 0xffff0000, v55
	s_waitcnt vmcnt(0)
	v_lshlrev_b32_e32 v235, 16, v44
	v_and_b32_e32 v44, 0xffff0000, v44
	v_lshlrev_b32_e32 v236, 16, v45
	v_and_b32_e32 v45, 0xffff0000, v45
	v_lshlrev_b32_e32 v237, 16, v46
	v_and_b32_e32 v46, 0xffff0000, v46
	v_lshlrev_b32_e32 v238, 16, v47
	v_and_b32_e32 v47, 0xffff0000, v47
	v_mul_f32_e32 v227, 0xbfb8aa3b, v227
	v_mul_f32_e32 v60, 0xbfb8aa3b, v60
	v_mul_f32_e32 v228, 0xbfb8aa3b, v228
	v_mul_f32_e32 v61, 0xbfb8aa3b, v61
	v_mul_f32_e32 v229, 0xbfb8aa3b, v229
	v_mul_f32_e32 v62, 0xbfb8aa3b, v62
	v_mul_f32_e32 v230, 0xbfb8aa3b, v230
	v_mul_f32_e32 v63, 0xbfb8aa3b, v63
	v_mul_f32_e32 v231, 0xbfb8aa3b, v231
	v_mul_f32_e32 v52, 0xbfb8aa3b, v52
	v_mul_f32_e32 v232, 0xbfb8aa3b, v232
	v_mul_f32_e32 v53, 0xbfb8aa3b, v53
	v_mul_f32_e32 v233, 0xbfb8aa3b, v233
	v_mul_f32_e32 v54, 0xbfb8aa3b, v54
	v_mul_f32_e32 v234, 0xbfb8aa3b, v234
	v_mul_f32_e32 v55, 0xbfb8aa3b, v55
	v_mul_f32_e32 v235, 0xbfb8aa3b, v235
	v_mul_f32_e32 v44, 0xbfb8aa3b, v44
	v_mul_f32_e32 v236, 0xbfb8aa3b, v236
	v_mul_f32_e32 v45, 0xbfb8aa3b, v45
	v_mul_f32_e32 v237, 0xbfb8aa3b, v237
	v_mul_f32_e32 v46, 0xbfb8aa3b, v46
	v_mul_f32_e32 v238, 0xbfb8aa3b, v238
	v_mul_f32_e32 v47, 0xbfb8aa3b, v47
	v_exp_f32_e32 v39, v39
	v_exp_f32_e32 v88, v88
	v_exp_f32_e32 v89, v89
	v_exp_f32_e32 v90, v90
	v_exp_f32_e32 v91, v91
	v_exp_f32_e32 v132, v132
	v_exp_f32_e32 v133, v133
	v_exp_f32_e32 v134, v134
	v_exp_f32_e32 v135, v135
	v_exp_f32_e32 v200, v200
	v_exp_f32_e32 v72, v72
	v_exp_f32_e32 v201, v201
	v_exp_f32_e32 v73, v73
	v_exp_f32_e32 v217, v217
	v_exp_f32_e32 v74, v74
	v_exp_f32_e32 v218, v218
	v_exp_f32_e32 v75, v75
	v_exp_f32_e32 v219, v219
	v_exp_f32_e32 v140, v140
	v_exp_f32_e32 v223, v223
	v_exp_f32_e32 v239, v40
	v_exp_f32_e32 v224, v224
	v_exp_f32_e32 v240, v41
	v_exp_f32_e32 v225, v225
	v_exp_f32_e32 v241, v42
	v_exp_f32_e32 v226, v226
	v_exp_f32_e32 v242, v43
	v_exp_f32_e32 v227, v227
	v_exp_f32_e32 v60, v60
	v_exp_f32_e32 v228, v228
	v_exp_f32_e32 v61, v61
	v_exp_f32_e32 v229, v229
	v_exp_f32_e32 v62, v62
	v_exp_f32_e32 v230, v230
	v_exp_f32_e32 v63, v63
	v_exp_f32_e32 v231, v231
	v_exp_f32_e32 v52, v52
	v_exp_f32_e32 v232, v232
	v_exp_f32_e32 v53, v53
	v_exp_f32_e32 v233, v233
	v_exp_f32_e32 v54, v54
	v_exp_f32_e32 v234, v234
	v_exp_f32_e32 v55, v55
	v_exp_f32_e32 v235, v235
	v_exp_f32_e32 v243, v44
	v_exp_f32_e32 v236, v236
	v_exp_f32_e32 v244, v45
	v_exp_f32_e32 v237, v237
	v_exp_f32_e32 v245, v46
	v_exp_f32_e32 v238, v238
	v_exp_f32_e32 v246, v47
	v_add_f32_e32 v28, 1.0, v28
	v_add_f32_e32 v29, 1.0, v29
	v_add_f32_e32 v30, 1.0, v30
	v_add_f32_e32 v31, 1.0, v31
	v_add_f32_e32 v36, 1.0, v36
	v_add_f32_e32 v37, 1.0, v37
	v_add_f32_e32 v38, 1.0, v38
	v_add_f32_e32 v39, 1.0, v39
	v_add_f32_e32 v40, 1.0, v88
	v_add_f32_e32 v41, 1.0, v89
	v_add_f32_e32 v42, 1.0, v90
	v_add_f32_e32 v43, 1.0, v91
	v_add_f32_e32 v44, 1.0, v132
	v_add_f32_e32 v45, 1.0, v133
	v_add_f32_e32 v46, 1.0, v134
	v_add_f32_e32 v47, 1.0, v135
	v_add_f32_e32 v88, 1.0, v200
	v_add_f32_e32 v72, 1.0, v72
	v_add_f32_e32 v89, 1.0, v201
	v_add_f32_e32 v73, 1.0, v73
	v_add_f32_e32 v90, 1.0, v217
	v_add_f32_e32 v74, 1.0, v74
	v_add_f32_e32 v91, 1.0, v218
	v_add_f32_e32 v75, 1.0, v75
	v_add_f32_e32 v132, 1.0, v219
	v_add_f32_e32 v133, 1.0, v140
	v_add_f32_e32 v134, 1.0, v220
	v_add_f32_e32 v135, 1.0, v141
	v_add_f32_e32 v140, 1.0, v221
	v_add_f32_e32 v141, 1.0, v142
	v_add_f32_e32 v142, 1.0, v222
	v_add_f32_e32 v200, 1.0, v223
	v_add_f32_e32 v201, 1.0, v239
	v_add_f32_e32 v217, 1.0, v224
	v_add_f32_e32 v218, 1.0, v240
	v_add_f32_e32 v219, 1.0, v225
	v_add_f32_e32 v220, 1.0, v241
	v_add_f32_e32 v221, 1.0, v226
	v_add_f32_e32 v222, 1.0, v242
	v_add_f32_e32 v223, 1.0, v227
	v_add_f32_e32 v224, 1.0, v60
	v_add_f32_e32 v225, 1.0, v228
	v_add_f32_e32 v226, 1.0, v61
	v_add_f32_e32 v227, 1.0, v229
	v_add_f32_e32 v228, 1.0, v62
	v_add_f32_e32 v229, 1.0, v230
	v_add_f32_e32 v230, 1.0, v63
	v_add_f32_e32 v231, 1.0, v231
	v_add_f32_e32 v239, 1.0, v52
	v_add_f32_e32 v232, 1.0, v232
	v_add_f32_e32 v240, 1.0, v53
	v_add_f32_e32 v233, 1.0, v233
	v_add_f32_e32 v241, 1.0, v54
	v_add_f32_e32 v234, 1.0, v234
	v_add_f32_e32 v242, 1.0, v55
	v_add_f32_e32 v235, 1.0, v235
	v_add_f32_e32 v243, 1.0, v243
	v_add_f32_e32 v236, 1.0, v236
	v_add_f32_e32 v244, 1.0, v244
	v_add_f32_e32 v237, 1.0, v237
	v_add_f32_e32 v245, 1.0, v245
	v_add_f32_e32 v238, 1.0, v238
	v_add_f32_e32 v246, 1.0, v246
	v_rcp_f32_e32 v28, v28
	v_rcp_f32_e32 v29, v29
	v_rcp_f32_e32 v30, v30
	v_rcp_f32_e32 v31, v31
	v_rcp_f32_e32 v36, v36
	v_rcp_f32_e32 v37, v37
	v_rcp_f32_e32 v38, v38
	v_rcp_f32_e32 v39, v39
	v_rcp_f32_e32 v40, v40
	v_rcp_f32_e32 v41, v41
	v_rcp_f32_e32 v42, v42
	v_rcp_f32_e32 v43, v43
	v_rcp_f32_e32 v44, v44
	v_rcp_f32_e32 v45, v45
	v_rcp_f32_e32 v46, v46
	v_rcp_f32_e32 v47, v47
	v_rcp_f32_e32 v52, v88
	v_rcp_f32_e32 v53, v72
	v_rcp_f32_e32 v54, v89
	v_rcp_f32_e32 v55, v73
	v_rcp_f32_e32 v60, v90
	v_rcp_f32_e32 v61, v74
	v_rcp_f32_e32 v62, v91
	v_rcp_f32_e32 v63, v75
	v_rcp_f32_e32 v72, v132
	v_rcp_f32_e32 v73, v133
	v_rcp_f32_e32 v74, v134
	v_rcp_f32_e32 v75, v135
	v_rcp_f32_e32 v88, v140
; __device__ __forceinline__ float bflo(unsigned w) { return __uint_as_float(w << 16); }
; __device__ __forceinline__ float bfhi(unsigned w) { return __uint_as_float(w & 0xffff0000u); }
; __device__ __forceinline__ float sigm(float x) { return frcp(1.f + fexp(-x)); }
; #define BG_STAGE(kk_, slot_) do { const int _n = (kk_) >> 2, _kt = (kk_) & 3; const int _so = (slot_) * STG; \
;         const bf16_t* _a = outs + ((size_t)_n * M + (size_t)pm * 256) * 256 + _kt * 64; const bf16_t* _b = wbr + ((size_t)_n * 1024 + (size_t)pn * 128) * 256 + _kt * 64; \
;         BG_LD(_so, _a); BG_LD(_so + HTB, _a + 128 * 256); BG_LDX(_so + 2 * HTB, _b, voffB); } while (0)
; #define BG_WAIT(n) asm volatile("s_waitcnt vmcnt(" #n ")" ::: "memory")
; #define BG_BAR() do { __builtin_amdgcn_s_barrier(); asm volatile("" ::: "memory"); } while (0)
; __device__ __forceinline__ void bgemm_phase(LAS unsigned char* lds, const bf16_t* outs, const bf16_t* wbr, const bf16_t* zg, bf16_t* merged) {
;     ...
;         for (int n = 0; n < 4; ++n) {
;             const int kk0 = n * 4;
;             BG_WAIT(6); BG_BAR(); { const int s2 = slot >= 1 ? slot - 1 : 2; BG_STAGE(kk0 + 2, s2); } BG_COMPUTE(slot); slot = slot == 2 ? 0 : slot + 1;
;             BG_WAIT(6); BG_BAR(); { const int s2 = slot >= 1 ? slot - 1 : 2; BG_STAGE(kk0 + 3, s2); } BG_COMPUTE(slot); slot = slot == 2 ? 0 : slot + 1;
;             BG_WAIT(6); BG_BAR(); if (n < 3) { const int s2 = slot >= 1 ? slot - 1 : 2; BG_STAGE(kk0 + 4, s2); } BG_COMPUTE(slot); slot = slot == 2 ? 0 : slot + 1;
;             if (n < 3) { BG_WAIT(6); } else { BG_WAIT(0); }
;     ...
;                     for (int g = 0; g < 2; ++g) { const u32x4 gq = gv[mi][g]; const int m2 = hf * 2 + mi;
;                         tot[m2][2 * g][0] += sigm(bflo(gq.x)) * acc[m2][2 * g][0]; tot[m2][2 * g][1] += sigm(bfhi(gq.x)) * acc[m2][2 * g][1];
;                         tot[m2][2 * g][2] += sigm(bflo(gq.y)) * acc[m2][2 * g][2]; tot[m2][2 * g][3] += sigm(bfhi(gq.y)) * acc[m2][2 * g][3];
;                         tot[m2][2 * g + 1][0] += sigm(bflo(gq.z)) * acc[m2][2 * g + 1][0]; tot[m2][2 * g + 1][1] += sigm(bfhi(gq.z)) * acc[m2][2 * g + 1][1];
;                         tot[m2][2 * g + 1][2] += sigm(bflo(gq.w)) * acc[m2][2 * g + 1][2]; tot[m2][2 * g + 1][3] += sigm(bfhi(gq.w)) * acc[m2][2 * g + 1][3];
;                         acc[m2][2 * g] = ZERO4; acc[m2][2 * g + 1] = ZERO4; }
	v_rcp_f32_e32 v89, v141
	v_rcp_f32_e32 v90, v142
	v_rcp_f32_e32 v91, v143
	v_rcp_f32_e32 v132, v200
	v_rcp_f32_e32 v133, v201
	v_rcp_f32_e32 v134, v217
	v_rcp_f32_e32 v135, v218
	v_rcp_f32_e32 v140, v219
	v_rcp_f32_e32 v141, v220
	v_rcp_f32_e32 v142, v221
	v_rcp_f32_e32 v143, v222
	v_rcp_f32_e32 v200, v223
	v_rcp_f32_e32 v201, v224
	v_rcp_f32_e32 v218, v225
	v_rcp_f32_e32 v219, v226
	v_rcp_f32_e32 v220, v227
	v_rcp_f32_e32 v221, v228
	v_rcp_f32_e32 v222, v229
	v_rcp_f32_e32 v223, v230
	v_rcp_f32_e32 v224, v231
	v_rcp_f32_e32 v225, v239
	v_rcp_f32_e32 v226, v232
	v_rcp_f32_e32 v227, v240
	v_rcp_f32_e32 v228, v233
	v_rcp_f32_e32 v229, v241
	v_rcp_f32_e32 v230, v234
	v_rcp_f32_e32 v231, v242
	v_rcp_f32_e32 v232, v235
	v_rcp_f32_e32 v233, v243
	v_rcp_f32_e32 v234, v236
	v_rcp_f32_e32 v235, v244
	v_rcp_f32_e32 v236, v237
	v_rcp_f32_e32 v237, v245
	v_rcp_f32_e32 v238, v238
	v_rcp_f32_e32 v239, v246
	v_pk_fma_f32 v[190:191], v[28:29], v[4:5], v[190:191]
	v_pk_fma_f32 v[192:193], v[30:31], v[6:7], v[192:193]
	v_pk_fma_f32 v[186:187], v[36:37], v[96:97], v[186:187]
	v_pk_fma_f32 v[188:189], v[38:39], v[98:99], v[188:189]
	v_pk_fma_f32 v[182:183], v[40:41], v[92:93], v[182:183]
	v_pk_fma_f32 v[184:185], v[42:43], v[94:95], v[184:185]
	v_pk_fma_f32 v[178:179], v[44:45], v[24:25], v[178:179]
	v_pk_fma_f32 v[180:181], v[46:47], v[26:27], v[180:181]
	v_pk_fma_f32 v[174:175], v[52:53], v[84:85], v[174:175]
	v_pk_fma_f32 v[176:177], v[54:55], v[86:87], v[176:177]
	v_pk_fma_f32 v[170:171], v[60:61], v[80:81], v[170:171]
	v_pk_fma_f32 v[172:173], v[62:63], v[82:83], v[172:173]
	v_pk_fma_f32 v[166:167], v[72:73], v[76:77], v[166:167]
	v_pk_fma_f32 v[168:169], v[74:75], v[78:79], v[168:169]
	v_pk_fma_f32 v[162:163], v[88:89], v[64:65], v[162:163]
	v_pk_fma_f32 v[164:165], v[90:91], v[66:67], v[164:165]
	v_pk_fma_f32 v[158:159], v[68:69], v[132:133], v[158:159]
	v_pk_fma_f32 v[160:161], v[70:71], v[134:135], v[160:161]
	v_pk_fma_f32 v[154:155], v[56:57], v[140:141], v[154:155]
	v_pk_fma_f32 v[156:157], v[58:59], v[142:143], v[156:157]
	v_pk_fma_f32 v[150:151], v[48:49], v[200:201], v[150:151]
	v_pk_fma_f32 v[152:153], v[50:51], v[218:219], v[152:153]
	v_pk_fma_f32 v[146:147], v[32:33], v[220:221], v[146:147]
	v_pk_fma_f32 v[148:149], v[34:35], v[222:223], v[148:149]
	v_pk_fma_f32 v[128:129], v[8:9], v[224:225], v[128:129]
	v_pk_fma_f32 v[130:131], v[10:11], v[226:227], v[130:131]
	v_pk_fma_f32 v[124:125], v[12:13], v[228:229], v[124:125]
	v_pk_fma_f32 v[126:127], v[14:15], v[230:231], v[126:127]
	v_pk_fma_f32 v[120:121], v[16:17], v[232:233], v[120:121]
	v_pk_fma_f32 v[122:123], v[18:19], v[234:235], v[122:123]
	v_pk_fma_f32 v[116:117], v[20:21], v[236:237], v[116:117]
	v_pk_fma_f32 v[118:119], v[22:23], v[238:239], v[118:119]
	s_cbranch_scc0 .LBB0_296
	s_add_u32 s16, s14, 0x1800100
	s_addc_u32 s17, s15, 0
	s_waitcnt vmcnt(6)
	s_barrier
	v_lshl_add_u64 v[4:5], s[16:17], 0, v[104:105]
	s_mov_b32 m0, s31
	v_add_u32_e32 v98, 0, v214
	global_load_lds_dwordx4 v[4:5], off
	v_lshl_add_u64 v[4:5], s[16:17], 0, v[100:101]
	s_add_u32 s16, s14, 0x1810100
	s_mov_b32 m0, s34
	s_addc_u32 s17, s15, 0
	global_load_lds_dwordx4 v[4:5], off
	v_lshl_add_u64 v[4:5], s[16:17], 0, v[104:105]
	s_add_i32 m0, s30, 0x1c000
	s_nop 0
	global_load_lds_dwordx4 v[4:5], off
	s_add_i32 m0, s30, 0x1e000
	v_lshl_add_u64 v[4:5], s[16:17], 0, v[100:101]
	s_add_u32 s16, s18, 0x180100
	s_addc_u32 s17, s19, 0
	global_load_lds_dwordx4 v[4:5], off
	v_lshl_add_u64 v[4:5], s[16:17], 0, v[102:103]
	s_add_i32 m0, s30, 0x20000
	s_nop 0
	global_load_lds_dwordx4 v[4:5], off
	v_lshl_add_u64 v[4:5], s[16:17], 0, v[0:1]
	s_add_i32 m0, s30, 0x22000
	s_add_u32 s16, s14, 0x1800180
	global_load_lds_dwordx4 v[4:5], off
	v_add_u32_e32 v4, 0, v3
	v_add_u32_e32 v5, 0, v145
	ds_read_b128 v[6:9], v4
	ds_read_b128 v[10:13], v4 offset:2048
	ds_read_b128 v[14:17], v4 offset:4096
	ds_read_b128 v[18:21], v4 offset:6144
	ds_read_b128 v[22:25], v5 offset:32768
	ds_read_b128 v[26:29], v5 offset:34816
	ds_read_b128 v[30:33], v5 offset:36864
	ds_read_b128 v[34:37], v5 offset:38912
	s_waitcnt lgkmcnt(0)
	v_mfma_f32_16x16x32_bf16 v[38:41], v[22:25], v[6:9], 0
	s_addc_u32 s17, s15, 0
	s_mov_b32 m0, s30
	s_add_u32 s14, s14, 0x1810180
	v_mfma_f32_16x16x32_bf16 v[42:45], v[26:29], v[6:9], 0
	s_addc_u32 s15, s15, 0
	v_mfma_f32_16x16x32_bf16 v[46:49], v[30:33], v[6:9], 0
	v_mfma_f32_16x16x32_bf16 v[6:9], v[34:37], v[6:9], 0
	v_mfma_f32_16x16x32_bf16 v[50:53], v[22:25], v[10:13], 0
	v_mfma_f32_16x16x32_bf16 v[54:57], v[26:29], v[10:13], 0
	v_mfma_f32_16x16x32_bf16 v[58:61], v[30:33], v[10:13], 0
	v_mfma_f32_16x16x32_bf16 v[10:13], v[34:37], v[10:13], 0
	v_mfma_f32_16x16x32_bf16 v[62:65], v[22:25], v[14:17], 0
	v_mfma_f32_16x16x32_bf16 v[66:69], v[26:29], v[14:17], 0
	v_mfma_f32_16x16x32_bf16 v[70:73], v[30:33], v[14:17], 0
	v_mfma_f32_16x16x32_bf16 v[14:17], v[34:37], v[14:17], 0
	v_mfma_f32_16x16x32_bf16 v[22:25], v[22:25], v[18:21], 0
	v_mfma_f32_16x16x32_bf16 v[26:29], v[26:29], v[18:21], 0
	v_mfma_f32_16x16x32_bf16 v[30:33], v[30:33], v[18:21], 0
	v_mfma_f32_16x16x32_bf16 v[18:21], v[34:37], v[18:21], 0
	ds_read_b128 v[34:37], v4 offset:1024
	ds_read_b128 v[74:77], v4 offset:3072
	ds_read_b128 v[78:81], v4 offset:5120
	ds_read_b128 v[82:85], v4 offset:7168
	ds_read_b128 v[86:89], v5 offset:33792
	ds_read_b128 v[90:93], v5 offset:35840
	ds_read_b128 v[94:97], v5 offset:37888
	ds_read_b128 v[194:197], v5 offset:39936
	s_waitcnt vmcnt(6)
	s_barrier
; #define BG_STAGE(kk_, slot_) do { const int _n = (kk_) >> 2, _kt = (kk_) & 3; const int _so = (slot_) * STG; \
;         const bf16_t* _a = outs + ((size_t)_n * M + (size_t)pm * 256) * 256 + _kt * 64; const bf16_t* _b = wbr + ((size_t)_n * 1024 + (size_t)pn * 128) * 256 + _kt * 64; \
;         BG_LD(_so, _a); BG_LD(_so + HTB, _a + 128 * 256); BG_LDX(_so + 2 * HTB, _b, voffB); } while (0)
; #define BG_WAIT(n) asm volatile("s_waitcnt vmcnt(" #n ")" ::: "memory")
; #define BG_BAR() do { __builtin_amdgcn_s_barrier(); asm volatile("" ::: "memory"); } while (0)
; __device__ __forceinline__ void bgemm_phase(LAS unsigned char* lds, const bf16_t* outs, const bf16_t* wbr, const bf16_t* zg, bf16_t* merged) {
;     ...
;         for (int n = 0; n < 4; ++n) {
;             const int kk0 = n * 4;
;             BG_WAIT(6); BG_BAR(); { const int s2 = slot >= 1 ? slot - 1 : 2; BG_STAGE(kk0 + 2, s2); } BG_COMPUTE(slot); slot = slot == 2 ? 0 : slot + 1;
;             BG_WAIT(6); BG_BAR(); { const int s2 = slot >= 1 ? slot - 1 : 2; BG_STAGE(kk0 + 3, s2); } BG_COMPUTE(slot); slot = slot == 2 ? 0 : slot + 1;
;             BG_WAIT(6); BG_BAR(); if (n < 3) { const int s2 = slot >= 1 ? slot - 1 : 2; BG_STAGE(kk0 + 4, s2); } BG_COMPUTE(slot); slot = slot == 2 ? 0 : slot + 1;
;             if (n < 3) { BG_WAIT(6); } else { BG_WAIT(0); }
;             BG_BAR(); if (n < 3) { const int s2 = slot >= 1 ? slot - 1 : 2; BG_STAGE(kk0 + 5, s2); }
;             size_t goff = (((size_t)n * 64 + pm) * 8 + pn) * 32768 + (size_t)(((wm * 4) * 4 + wn * 2) * 64 + fq * 16 + fr) * 8;
;             asm volatile("" : "+v"(goff) :: "memory");
;             const bf16_t* gp0 = zg + goff;
;             u32x4 gv[2][2];
; #pragma unroll
;             for (int mi = 0; mi < 2; ++mi)
; #pragma unroll
;                 for (int g = 0; g < 2; ++g) gv[mi][g] = *(const u32x4*)(gp0 + (mi * 4 + g) * 512);
;             BG_COMPUTE(slot); slot = slot == 2 ? 0 : slot + 1;
	s_waitcnt lgkmcnt(0)
	v_mfma_f32_16x16x32_bf16 v[38:41], v[86:89], v[34:37], v[38:41]
	v_mfma_f32_16x16x32_bf16 v[42:45], v[90:93], v[34:37], v[42:45]
	v_mfma_f32_16x16x32_bf16 v[46:49], v[94:97], v[34:37], v[46:49]
	v_mfma_f32_16x16x32_bf16 v[6:9], v[194:197], v[34:37], v[6:9]
	v_mfma_f32_16x16x32_bf16 v[34:37], v[86:89], v[74:77], v[50:53]
	v_mfma_f32_16x16x32_bf16 v[50:53], v[90:93], v[74:77], v[54:57]
	v_mfma_f32_16x16x32_bf16 v[54:57], v[94:97], v[74:77], v[58:61]
	v_mfma_f32_16x16x32_bf16 v[58:61], v[86:89], v[78:81], v[62:65]
	v_mfma_f32_16x16x32_bf16 v[62:65], v[90:93], v[78:81], v[66:69]
	v_mfma_f32_16x16x32_bf16 v[66:69], v[94:97], v[78:81], v[70:73]
	s_nop 2
	v_lshl_add_u64 v[70:71], s[16:17], 0, v[104:105]
	global_load_lds_dwordx4 v[70:71], off
	v_lshl_add_u64 v[70:71], s[16:17], 0, v[100:101]
	s_mov_b32 m0, s42
	v_mfma_f32_16x16x32_bf16 v[10:13], v[194:197], v[74:77], v[10:13]
	global_load_lds_dwordx4 v[70:71], off
	v_lshl_add_u64 v[70:71], s[14:15], 0, v[104:105]
	s_mov_b32 m0, s41
	v_mfma_f32_16x16x32_bf16 v[14:17], v[194:197], v[78:81], v[14:17]
	global_load_lds_dwordx4 v[70:71], off
	v_lshl_add_u64 v[70:71], s[14:15], 0, v[100:101]
	s_add_u32 s14, s18, 0x180180
	s_mov_b32 m0, s40
	s_addc_u32 s15, s19, 0
	global_load_lds_dwordx4 v[70:71], off
	v_lshl_add_u64 v[70:71], s[14:15], 0, v[102:103]
	s_mov_b32 m0, s39
	v_mfma_f32_16x16x32_bf16 v[22:25], v[86:89], v[82:85], v[22:25]
	global_load_lds_dwordx4 v[70:71], off
	v_lshl_add_u64 v[70:71], s[14:15], 0, v[0:1]
	s_mov_b32 m0, s38
	v_mfma_f32_16x16x32_bf16 v[26:29], v[90:93], v[82:85], v[26:29]
	global_load_lds_dwordx4 v[70:71], off
	s_add_i32 s14, 0, 0x18000
	v_mfma_f32_16x16x32_bf16 v[30:33], v[94:97], v[82:85], v[30:33]
	v_add_u32_e32 v99, s14, v3
	s_add_u32 s12, s12, s37
	s_addc_u32 s13, s13, 0
	v_mfma_f32_16x16x32_bf16 v[18:21], v[194:197], v[82:85], v[18:21]
	ds_read_b128 v[70:73], v4 offset:49152
	ds_read_b128 v[74:77], v4 offset:51200
	ds_read_b128 v[78:81], v4 offset:53248
	ds_read_b128 v[82:85], v4 offset:55296
	ds_read_b128 v[86:89], v98 offset:49152
	ds_read_b128 v[90:93], v98 offset:51200
	ds_read_b128 v[94:97], v98 offset:53248
	ds_read_b128 v[194:197], v98 offset:55296
	s_waitcnt lgkmcnt(0)
	v_mfma_f32_16x16x32_bf16 v[38:41], v[86:89], v[70:73], v[38:41]
	v_mfma_f32_16x16x32_bf16 v[42:45], v[90:93], v[70:73], v[42:45]
	v_mfma_f32_16x16x32_bf16 v[46:49], v[94:97], v[70:73], v[46:49]
	v_mfma_f32_16x16x32_bf16 v[6:9], v[194:197], v[70:73], v[6:9]
	v_mfma_f32_16x16x32_bf16 v[34:37], v[86:89], v[74:77], v[34:37]
	v_mfma_f32_16x16x32_bf16 v[50:53], v[90:93], v[74:77], v[50:53]
	v_mfma_f32_16x16x32_bf16 v[54:57], v[94:97], v[74:77], v[54:57]
	v_mfma_f32_16x16x32_bf16 v[10:13], v[194:197], v[74:77], v[10:13]
	v_mfma_f32_16x16x32_bf16 v[58:61], v[86:89], v[78:81], v[58:61]
	v_mfma_f32_16x16x32_bf16 v[62:65], v[90:93], v[78:81], v[62:65]
	v_mfma_f32_16x16x32_bf16 v[66:69], v[94:97], v[78:81], v[66:69]
	v_mfma_f32_16x16x32_bf16 v[14:17], v[194:197], v[78:81], v[14:17]
	v_mfma_f32_16x16x32_bf16 v[22:25], v[86:89], v[82:85], v[22:25]
	v_mfma_f32_16x16x32_bf16 v[26:29], v[90:93], v[82:85], v[26:29]
	v_mfma_f32_16x16x32_bf16 v[30:33], v[94:97], v[82:85], v[30:33]
	v_mfma_f32_16x16x32_bf16 v[18:21], v[194:197], v[82:85], v[18:21]
	ds_read_b128 v[70:73], v4 offset:50176
	ds_read_b128 v[74:77], v4 offset:52224
	ds_read_b128 v[78:81], v4 offset:54272
	ds_read_b128 v[82:85], v4 offset:56320
	ds_read_b128 v[86:89], v98 offset:50176
	ds_read_b128 v[90:93], v98 offset:52224
	ds_read_b128 v[94:97], v98 offset:54272
	ds_read_b128 v[194:197], v98 offset:56320
	s_waitcnt vmcnt(6)
	s_barrier
	v_add_u32_e32 v98, s14, v214
	s_waitcnt lgkmcnt(0)
	v_mfma_f32_16x16x32_bf16 v[38:41], v[86:89], v[70:73], v[38:41]
	v_mfma_f32_16x16x32_bf16 v[42:45], v[90:93], v[70:73], v[42:45]
	v_mfma_f32_16x16x32_bf16 v[46:49], v[94:97], v[70:73], v[46:49]
	v_mfma_f32_16x16x32_bf16 v[6:9], v[194:197], v[70:73], v[6:9]
	v_mfma_f32_16x16x32_bf16 v[34:37], v[86:89], v[74:77], v[34:37]
	v_mfma_f32_16x16x32_bf16 v[50:53], v[90:93], v[74:77], v[50:53]
	v_mfma_f32_16x16x32_bf16 v[54:57], v[94:97], v[74:77], v[54:57]
	v_mfma_f32_16x16x32_bf16 v[10:13], v[194:197], v[74:77], v[10:13]
	v_mfma_f32_16x16x32_bf16 v[58:61], v[86:89], v[78:81], v[58:61]
	v_mfma_f32_16x16x32_bf16 v[62:65], v[90:93], v[78:81], v[62:65]
	v_mfma_f32_16x16x32_bf16 v[66:69], v[94:97], v[78:81], v[66:69]
	v_mfma_f32_16x16x32_bf16 v[14:17], v[194:197], v[78:81], v[14:17]
	v_mfma_f32_16x16x32_bf16 v[22:25], v[86:89], v[82:85], v[22:25]
	v_mfma_f32_16x16x32_bf16 v[26:29], v[90:93], v[82:85], v[26:29]
	v_mfma_f32_16x16x32_bf16 v[30:33], v[94:97], v[82:85], v[30:33]
	v_mfma_f32_16x16x32_bf16 v[18:21], v[194:197], v[82:85], v[18:21]
	ds_read_b128 v[70:73], v98 offset:7168
	ds_read_b128 v[74:77], v98 offset:5120
	ds_read_b128 v[78:81], v98 offset:3072
	ds_read_b128 v[82:85], v98 offset:1024
	ds_read_b128 v[86:89], v99 offset:7168
	ds_read_b128 v[90:93], v99 offset:5120
	ds_read_b128 v[94:97], v99 offset:3072
	ds_read_b128 v[194:197], v99 offset:1024
	ds_read_b128 v[198:201], v98 offset:6144
	ds_read_b128 v[218:221], v98 offset:4096
	ds_read_b128 v[222:225], v98 offset:2048
	ds_read_b128 v[226:229], v98
	ds_read_b128 v[230:233], v99 offset:6144
	ds_read_b128 v[234:237], v99 offset:4096
	ds_read_b128 v[238:241], v99 offset:2048
	ds_read_b128 v[242:245], v99
	s_waitcnt vmcnt(0)
	s_waitcnt lgkmcnt(0)
	v_mfma_f32_16x16x32_bf16 v[38:41], v[226:229], v[242:245], v[38:41]
	s_barrier
; #define BG_STAGE(kk_, slot_) do { const int _n = (kk_) >> 2, _kt = (kk_) & 3; const int _so = (slot_) * STG; \
;         const bf16_t* _a = outs + ((size_t)_n * M + (size_t)pm * 256) * 256 + _kt * 64; const bf16_t* _b = wbr + ((size_t)_n * 1024 + (size_t)pn * 128) * 256 + _kt * 64; \
;         BG_LD(_so, _a); BG_LD(_so + HTB, _a + 128 * 256); BG_LDX(_so + 2 * HTB, _b, voffB); } while (0)
; #define BG_BAR() do { __builtin_amdgcn_s_barrier(); asm volatile("" ::: "memory"); } while (0)
; __device__ __forceinline__ void bgemm_phase(LAS unsigned char* lds, const bf16_t* outs, const bf16_t* wbr, const bf16_t* zg, bf16_t* merged) {
;     ...
;             BG_BAR(); if (n < 3) { const int s2 = slot >= 1 ? slot - 1 : 2; BG_STAGE(kk0 + 5, s2); }
;             size_t goff = (((size_t)n * 64 + pm) * 8 + pn) * 32768 + (size_t)(((wm * 4) * 4 + wn * 2) * 64 + fq * 16 + fr) * 8;
;             asm volatile("" : "+v"(goff) :: "memory");
;             const bf16_t* gp0 = zg + goff;
;             u32x4 gv[2][2];
; #pragma unroll
;             for (int mi = 0; mi < 2; ++mi)
; #pragma unroll
;                 for (int g = 0; g < 2; ++g) gv[mi][g] = *(const u32x4*)(gp0 + (mi * 4 + g) * 512);
;             BG_COMPUTE(slot); slot = slot == 2 ? 0 : slot + 1;
; #pragma unroll
;             for (int hf = 0; hf < 2; ++hf) {
;                 u32x4 gn[2][2];
;                 if (hf == 0) {
; #pragma unroll
;                     for (int mi = 0; mi < 2; ++mi)
; #pragma unroll
;                         for (int g = 0; g < 2; ++g) gn[mi][g] = *(const u32x4*)(gp0 + ((2 + mi) * 4 + g) * 512);
	v_mfma_f32_16x16x32_bf16 v[42:45], v[222:225], v[242:245], v[42:45]
	v_mfma_f32_16x16x32_bf16 v[46:49], v[218:221], v[242:245], v[46:49]
	v_mfma_f32_16x16x32_bf16 v[6:9], v[198:201], v[242:245], v[6:9]
	v_mfma_f32_16x16x32_bf16 v[50:53], v[222:225], v[238:241], v[50:53]
	v_mfma_f32_16x16x32_bf16 v[34:37], v[226:229], v[238:241], v[34:37]
	v_mfma_f32_16x16x32_bf16 v[54:57], v[218:221], v[238:241], v[54:57]
	v_mfma_f32_16x16x32_bf16 v[10:13], v[198:201], v[238:241], v[10:13]
	v_mfma_f32_16x16x32_bf16 v[58:61], v[226:229], v[234:237], v[58:61]
	v_mfma_f32_16x16x32_bf16 v[62:65], v[222:225], v[234:237], v[62:65]
	v_mfma_f32_16x16x32_bf16 v[66:69], v[218:221], v[234:237], v[66:69]
	v_mfma_f32_16x16x32_bf16 v[14:17], v[198:201], v[234:237], v[14:17]
	v_mfma_f32_16x16x32_bf16 v[22:25], v[226:229], v[230:233], v[22:25]
	v_mfma_f32_16x16x32_bf16 v[26:29], v[222:225], v[230:233], v[26:29]
	v_mfma_f32_16x16x32_bf16 v[30:33], v[218:221], v[230:233], v[30:33]
	v_mfma_f32_16x16x32_bf16 v[18:21], v[198:201], v[230:233], v[18:21]
	v_mfma_f32_16x16x32_bf16 v[38:41], v[82:85], v[194:197], v[38:41]
	v_mfma_f32_16x16x32_bf16 v[42:45], v[78:81], v[194:197], v[42:45]
	v_mfma_f32_16x16x32_bf16 v[46:49], v[74:77], v[194:197], v[46:49]
	v_mfma_f32_16x16x32_bf16 v[6:9], v[70:73], v[194:197], v[6:9]
	v_mfma_f32_16x16x32_bf16 v[194:197], v[78:81], v[94:97], v[50:53]
	s_nop 2
	v_lshl_add_u64 v[50:51], s[12:13], 0, v[106:107]
	s_mov_b64 s[12:13], 0x3000000
	v_lshl_add_u64 v[50:51], v[50:51], 0, s[12:13]
	v_mfma_f32_16x16x32_bf16 v[34:37], v[82:85], v[94:97], v[34:37]
	v_lshl_add_u64 v[140:141], v[50:51], 1, s[8:9]
	v_add_co_u32_e32 v50, vcc, s80, v140
	v_mfma_f32_16x16x32_bf16 v[198:201], v[74:77], v[94:97], v[54:57]
	s_nop 0
	v_addc_co_u32_e32 v51, vcc, 0, v141, vcc
	v_add_co_u32_e32 v142, vcc, s81, v140
	v_mfma_f32_16x16x32_bf16 v[10:13], v[70:73], v[94:97], v[10:13]
	s_nop 0
	v_addc_co_u32_e32 v143, vcc, 0, v141, vcc
	s_mov_b32 s12, s90
	v_mfma_f32_16x16x32_bf16 v[56:59], v[82:85], v[90:93], v[58:61]
	v_mfma_f32_16x16x32_bf16 v[60:63], v[78:81], v[90:93], v[62:65]
	v_mfma_f32_16x16x32_bf16 v[94:97], v[74:77], v[90:93], v[66:69]
	v_mfma_f32_16x16x32_bf16 v[14:17], v[70:73], v[90:93], v[14:17]
	v_mfma_f32_16x16x32_bf16 v[22:25], v[82:85], v[86:89], v[22:25]
	v_mfma_f32_16x16x32_bf16 v[26:29], v[78:81], v[86:89], v[26:29]
	v_mfma_f32_16x16x32_bf16 v[30:33], v[74:77], v[86:89], v[30:33]
	v_mfma_f32_16x16x32_bf16 v[18:21], v[70:73], v[86:89], v[18:21]
	global_load_dwordx4 v[88:91], v[140:141], off
	global_load_dwordx4 v[76:79], v[140:141], off offset:1024
	global_load_dwordx4 v[64:67], v[142:143], off offset:-4096
	global_load_dwordx4 v[52:55], v[50:51], off offset:1024
	ds_read_b128 v[68:71], v4
	ds_read_b128 v[72:75], v4 offset:2048
	ds_read_b128 v[80:83], v4 offset:4096
	ds_read_b128 v[84:87], v4 offset:6144
	ds_read_b128 v[218:221], v5 offset:32768
	ds_read_b128 v[222:225], v5 offset:34816
	ds_read_b128 v[226:229], v5 offset:36864
	ds_read_b128 v[230:233], v5 offset:38912
	s_waitcnt lgkmcnt(0)
	v_mfma_f32_16x16x32_bf16 v[38:41], v[218:221], v[68:71], v[38:41]
	v_mfma_f32_16x16x32_bf16 v[42:45], v[222:225], v[68:71], v[42:45]
	v_mfma_f32_16x16x32_bf16 v[46:49], v[226:229], v[68:71], v[46:49]
	v_mfma_f32_16x16x32_bf16 v[6:9], v[230:233], v[68:71], v[6:9]
	v_mfma_f32_16x16x32_bf16 v[34:37], v[218:221], v[72:75], v[34:37]
	v_mfma_f32_16x16x32_bf16 v[68:71], v[222:225], v[72:75], v[194:197]
	v_mfma_f32_16x16x32_bf16 v[194:197], v[226:229], v[72:75], v[198:201]
	v_mfma_f32_16x16x32_bf16 v[10:13], v[230:233], v[72:75], v[10:13]
	v_mfma_f32_16x16x32_bf16 v[198:201], v[218:221], v[80:83], v[56:59]
	v_mfma_f32_16x16x32_bf16 v[234:237], v[222:225], v[80:83], v[60:63]
	v_mfma_f32_16x16x32_bf16 v[238:241], v[226:229], v[80:83], v[94:97]
	v_mfma_f32_16x16x32_bf16 v[14:17], v[230:233], v[80:83], v[14:17]
	v_mfma_f32_16x16x32_bf16 v[22:25], v[218:221], v[84:87], v[22:25]
	v_mfma_f32_16x16x32_bf16 v[218:221], v[222:225], v[84:87], v[26:29]
	v_mfma_f32_16x16x32_bf16 v[222:225], v[226:229], v[84:87], v[30:33]
	v_mfma_f32_16x16x32_bf16 v[226:229], v[230:233], v[84:87], v[18:21]
	s_nop 2
	ds_read_b128 v[18:21], v4 offset:1024
	ds_read_b128 v[26:29], v4 offset:3072
	ds_read_b128 v[30:33], v4 offset:5120
	ds_read_b128 v[230:233], v4 offset:7168
	ds_read_b128 v[242:245], v5 offset:33792
	ds_read_b128 v[246:249], v5 offset:35840
	ds_read_b128 v[250:253], v5 offset:37888
	ds_read_b128 v[132:135], v5 offset:39936
	s_waitcnt lgkmcnt(0)
	v_mfma_f32_16x16x32_bf16 v[96:99], v[242:245], v[18:21], v[38:41]
	v_mfma_f32_16x16x32_bf16 v[92:95], v[246:249], v[18:21], v[42:45]
	v_mfma_f32_16x16x32_bf16 v[84:87], v[250:253], v[18:21], v[46:49]
	v_mfma_f32_16x16x32_bf16 v[80:83], v[132:135], v[18:21], v[6:9]
	v_mfma_f32_16x16x32_bf16 v[72:75], v[242:245], v[26:29], v[34:37]
	s_nop 1
	v_add_co_u32_e32 v8, vcc, s82, v140
	v_mfma_f32_16x16x32_bf16 v[68:71], v[246:249], v[26:29], v[68:71]
	s_nop 0
	v_addc_co_u32_e32 v9, vcc, 0, v141, vcc
	v_mfma_f32_16x16x32_bf16 v[60:63], v[250:253], v[26:29], v[194:197]
	v_mfma_f32_16x16x32_bf16 v[56:59], v[132:135], v[26:29], v[10:13]
	v_mfma_f32_16x16x32_bf16 v[48:51], v[242:245], v[30:33], v[198:201]
	v_mfma_f32_16x16x32_bf16 v[40:43], v[246:249], v[30:33], v[234:237]
	v_mfma_f32_16x16x32_bf16 v[36:39], v[250:253], v[30:33], v[238:241]
	v_mfma_f32_16x16x32_bf16 v[28:31], v[132:135], v[30:33], v[14:17]
	global_load_dwordx4 v[44:47], v[142:143], off
	global_load_dwordx4 v[32:35], v[142:143], off offset:1024
	v_mfma_f32_16x16x32_bf16 v[4:7], v[132:135], v[230:233], v[226:229]
	s_waitcnt vmcnt(0)
; __device__ __forceinline__ float bflo(unsigned w) { return __uint_as_float(w << 16); }
; __device__ __forceinline__ float bfhi(unsigned w) { return __uint_as_float(w & 0xffff0000u); }
; __device__ __forceinline__ float sigm(float x) { return frcp(1.f + fexp(-x)); }
; __device__ __forceinline__ void bgemm_phase(LAS unsigned char* lds, const bf16_t* outs, const bf16_t* wbr, const bf16_t* zg, bf16_t* merged) {
;     ...
; #pragma unroll
;                 for (int mi = 0; mi < 2; ++mi)
; #pragma unroll
;                     for (int g = 0; g < 2; ++g) { const u32x4 gq = gv[mi][g]; const int m2 = hf * 2 + mi;
;                         tot[m2][2 * g][0] += sigm(bflo(gq.x)) * acc[m2][2 * g][0]; tot[m2][2 * g][1] += sigm(bfhi(gq.x)) * acc[m2][2 * g][1];
;                         tot[m2][2 * g][2] += sigm(bflo(gq.y)) * acc[m2][2 * g][2]; tot[m2][2 * g][3] += sigm(bfhi(gq.y)) * acc[m2][2 * g][3];
;                         tot[m2][2 * g + 1][0] += sigm(bflo(gq.z)) * acc[m2][2 * g + 1][0]; tot[m2][2 * g + 1][1] += sigm(bfhi(gq.z)) * acc[m2][2 * g + 1][1];
;                         tot[m2][2 * g + 1][2] += sigm(bflo(gq.w)) * acc[m2][2 * g + 1][2]; tot[m2][2 * g + 1][3] += sigm(bfhi(gq.w)) * acc[m2][2 * g + 1][3];
;                         acc[m2][2 * g] = ZERO4; acc[m2][2 * g + 1] = ZERO4; }
	v_lshlrev_b32_e32 v132, 16, v88
	v_and_b32_e32 v88, 0xffff0000, v88
	v_mul_f32_e32 v88, 0xbfb8aa3b, v88
	v_exp_f32_e32 v88, v88
	v_mfma_f32_16x16x32_bf16 v[24:27], v[242:245], v[230:233], v[22:25]
	s_nop 2
	global_load_dwordx4 v[20:23], v[8:9], off
	s_nop 0
	global_load_dwordx4 v[8:11], v[8:9], off offset:1024
	v_mul_f32_e32 v132, 0xbfb8aa3b, v132
	v_add_f32_e32 v88, 1.0, v88
	v_rcp_f32_e32 v88, v88
	v_mfma_f32_16x16x32_bf16 v[16:19], v[246:249], v[230:233], v[218:221]
	v_exp_f32_e32 v132, v132
	v_fmac_f32_e32 v191, v88, v97
	v_lshlrev_b32_e32 v88, 16, v89
	v_and_b32_e32 v89, 0xffff0000, v89
	v_mul_f32_e32 v89, 0xbfb8aa3b, v89
	v_exp_f32_e32 v89, v89
	v_mfma_f32_16x16x32_bf16 v[12:15], v[250:253], v[230:233], v[222:225]
	v_mul_f32_e32 v88, 0xbfb8aa3b, v88
	v_exp_f32_e32 v88, v88
	v_add_f32_e32 v89, 1.0, v89
	v_rcp_f32_e32 v89, v89
	v_add_f32_e32 v132, 1.0, v132
	v_rcp_f32_e32 v132, v132
	v_add_f32_e32 v88, 1.0, v88
	v_fmac_f32_e32 v193, v89, v99
	v_lshlrev_b32_e32 v89, 16, v90
	v_and_b32_e32 v90, 0xffff0000, v90
	v_mul_f32_e32 v90, 0xbfb8aa3b, v90
	v_exp_f32_e32 v90, v90
	v_mul_f32_e32 v89, 0xbfb8aa3b, v89
	v_exp_f32_e32 v89, v89
	v_rcp_f32_e32 v88, v88
	v_add_f32_e32 v90, 1.0, v90
	v_rcp_f32_e32 v90, v90
	v_add_f32_e32 v89, 1.0, v89
	v_rcp_f32_e32 v89, v89
	v_fma_f32 v96, v132, v96, v190
	v_fmac_f32_e32 v187, v90, v93
	v_lshlrev_b32_e32 v90, 16, v91
	v_and_b32_e32 v91, 0xffff0000, v91
	v_mul_f32_e32 v91, 0xbfb8aa3b, v91
	v_exp_f32_e32 v91, v91
	v_mul_f32_e32 v90, 0xbfb8aa3b, v90
	v_exp_f32_e32 v90, v90
	v_fma_f32 v88, v88, v98, v192
	v_add_f32_e32 v91, 1.0, v91
	v_rcp_f32_e32 v91, v91
	v_add_f32_e32 v90, 1.0, v90
	v_rcp_f32_e32 v90, v90
	v_fma_f32 v89, v89, v92, v186
	v_fmac_f32_e32 v189, v91, v95
	v_lshlrev_b32_e32 v91, 16, v76
	v_and_b32_e32 v76, 0xffff0000, v76
	v_mul_f32_e32 v76, 0xbfb8aa3b, v76
	v_exp_f32_e32 v76, v76
	v_mul_f32_e32 v91, 0xbfb8aa3b, v91
	v_exp_f32_e32 v91, v91
	v_fma_f32 v90, v90, v94, v188
	v_add_f32_e32 v76, 1.0, v76
	v_rcp_f32_e32 v76, v76
	v_add_f32_e32 v91, 1.0, v91
	v_rcp_f32_e32 v91, v91
	v_fmac_f32_e32 v183, v76, v85
	v_lshlrev_b32_e32 v76, 16, v77
	v_and_b32_e32 v77, 0xffff0000, v77
	v_mul_f32_e32 v77, 0xbfb8aa3b, v77
	v_exp_f32_e32 v77, v77
	v_mul_f32_e32 v76, 0xbfb8aa3b, v76
	v_exp_f32_e32 v76, v76
	v_fma_f32 v84, v91, v84, v182
	v_add_f32_e32 v77, 1.0, v77
	v_rcp_f32_e32 v77, v77
	v_add_f32_e32 v76, 1.0, v76
	v_rcp_f32_e32 v76, v76
	v_fmac_f32_e32 v185, v77, v87
	v_lshlrev_b32_e32 v77, 16, v78
	v_and_b32_e32 v78, 0xffff0000, v78
	v_mul_f32_e32 v78, 0xbfb8aa3b, v78
	v_exp_f32_e32 v78, v78
	v_mul_f32_e32 v77, 0xbfb8aa3b, v77
	v_exp_f32_e32 v77, v77
	v_fma_f32 v76, v76, v86, v184
	v_add_f32_e32 v78, 1.0, v78
	v_rcp_f32_e32 v78, v78
	v_add_f32_e32 v77, 1.0, v77
	v_rcp_f32_e32 v77, v77
	v_fmac_f32_e32 v179, v78, v81
	v_lshlrev_b32_e32 v78, 16, v79
	v_and_b32_e32 v79, 0xffff0000, v79
	v_mul_f32_e32 v79, 0xbfb8aa3b, v79
	v_exp_f32_e32 v79, v79
	v_mul_f32_e32 v78, 0xbfb8aa3b, v78
	v_exp_f32_e32 v78, v78
	v_fma_f32 v77, v77, v80, v178
	v_add_f32_e32 v79, 1.0, v79
	v_rcp_f32_e32 v79, v79
	v_add_f32_e32 v78, 1.0, v78
	v_rcp_f32_e32 v78, v78
	v_fmac_f32_e32 v181, v79, v83
	v_lshlrev_b32_e32 v79, 16, v64
	v_and_b32_e32 v64, 0xffff0000, v64
	v_mul_f32_e32 v64, 0xbfb8aa3b, v64
	v_exp_f32_e32 v64, v64
	v_mul_f32_e32 v79, 0xbfb8aa3b, v79
	v_exp_f32_e32 v79, v79
	v_fma_f32 v78, v78, v82, v180
	v_add_f32_e32 v64, 1.0, v64
	v_rcp_f32_e32 v64, v64
	v_add_f32_e32 v79, 1.0, v79
	v_rcp_f32_e32 v79, v79
	v_fmac_f32_e32 v175, v64, v73
	v_lshlrev_b32_e32 v64, 16, v65
	v_and_b32_e32 v65, 0xffff0000, v65
	v_mul_f32_e32 v65, 0xbfb8aa3b, v65
	v_exp_f32_e32 v65, v65
	v_mul_f32_e32 v64, 0xbfb8aa3b, v64
	v_exp_f32_e32 v64, v64
	v_fma_f32 v72, v79, v72, v174
	v_add_f32_e32 v65, 1.0, v65
	v_rcp_f32_e32 v65, v65
	v_add_f32_e32 v64, 1.0, v64
	v_rcp_f32_e32 v64, v64
	v_fmac_f32_e32 v177, v65, v75
	v_lshlrev_b32_e32 v65, 16, v66
	v_and_b32_e32 v66, 0xffff0000, v66
	v_mul_f32_e32 v66, 0xbfb8aa3b, v66
	v_exp_f32_e32 v66, v66
	v_mul_f32_e32 v65, 0xbfb8aa3b, v65
	v_exp_f32_e32 v65, v65
	v_fma_f32 v64, v64, v74, v176
	v_add_f32_e32 v66, 1.0, v66
	v_rcp_f32_e32 v66, v66
	v_add_f32_e32 v65, 1.0, v65
	v_rcp_f32_e32 v65, v65
	v_fmac_f32_e32 v171, v66, v69
	v_lshlrev_b32_e32 v66, 16, v67
	v_and_b32_e32 v67, 0xffff0000, v67
	v_mul_f32_e32 v67, 0xbfb8aa3b, v67
	v_exp_f32_e32 v67, v67
	v_mul_f32_e32 v66, 0xbfb8aa3b, v66
	v_exp_f32_e32 v66, v66
	v_fma_f32 v65, v65, v68, v170
	v_add_f32_e32 v67, 1.0, v67
	v_rcp_f32_e32 v67, v67
	v_add_f32_e32 v66, 1.0, v66
	v_rcp_f32_e32 v66, v66
	v_fmac_f32_e32 v173, v67, v71
	v_lshlrev_b32_e32 v67, 16, v52
	v_and_b32_e32 v52, 0xffff0000, v52
	v_mul_f32_e32 v52, 0xbfb8aa3b, v52
	v_exp_f32_e32 v52, v52
	v_mul_f32_e32 v67, 0xbfb8aa3b, v67
	v_exp_f32_e32 v67, v67
	v_fma_f32 v66, v66, v70, v172
	v_add_f32_e32 v52, 1.0, v52
	v_rcp_f32_e32 v52, v52
	v_add_f32_e32 v67, 1.0, v67
	v_rcp_f32_e32 v67, v67
	v_fmac_f32_e32 v167, v52, v61
	v_lshlrev_b32_e32 v52, 16, v53
	v_and_b32_e32 v53, 0xffff0000, v53
	v_mul_f32_e32 v53, 0xbfb8aa3b, v53
	v_exp_f32_e32 v53, v53
	v_mul_f32_e32 v52, 0xbfb8aa3b, v52
	v_exp_f32_e32 v52, v52
	v_fma_f32 v60, v67, v60, v166
	v_add_f32_e32 v53, 1.0, v53
	v_rcp_f32_e32 v53, v53
	v_add_f32_e32 v52, 1.0, v52
	v_rcp_f32_e32 v52, v52
	v_fmac_f32_e32 v169, v53, v63
	v_lshlrev_b32_e32 v53, 16, v54
	v_and_b32_e32 v54, 0xffff0000, v54
	v_mul_f32_e32 v54, 0xbfb8aa3b, v54
	v_exp_f32_e32 v54, v54
	v_mul_f32_e32 v53, 0xbfb8aa3b, v53
	v_exp_f32_e32 v53, v53
	v_fma_f32 v52, v52, v62, v168
	v_add_f32_e32 v54, 1.0, v54
	v_rcp_f32_e32 v54, v54
	v_add_f32_e32 v53, 1.0, v53
	v_rcp_f32_e32 v53, v53
	v_fmac_f32_e32 v163, v54, v57
; __device__ __forceinline__ float bflo(unsigned w) { return __uint_as_float(w << 16); }
; __device__ __forceinline__ float bfhi(unsigned w) { return __uint_as_float(w & 0xffff0000u); }
; __device__ __forceinline__ float sigm(float x) { return frcp(1.f + fexp(-x)); }
; __device__ __forceinline__ void bgemm_phase(LAS unsigned char* lds, const bf16_t* outs, const bf16_t* wbr, const bf16_t* zg, bf16_t* merged) {
;     ...
; #pragma unroll
;                 for (int mi = 0; mi < 2; ++mi)
; #pragma unroll
;                     for (int g = 0; g < 2; ++g) { const u32x4 gq = gv[mi][g]; const int m2 = hf * 2 + mi;
;                         tot[m2][2 * g][0] += sigm(bflo(gq.x)) * acc[m2][2 * g][0]; tot[m2][2 * g][1] += sigm(bfhi(gq.x)) * acc[m2][2 * g][1];
;                         tot[m2][2 * g][2] += sigm(bflo(gq.y)) * acc[m2][2 * g][2]; tot[m2][2 * g][3] += sigm(bfhi(gq.y)) * acc[m2][2 * g][3];
;                         tot[m2][2 * g + 1][0] += sigm(bflo(gq.z)) * acc[m2][2 * g + 1][0]; tot[m2][2 * g + 1][1] += sigm(bfhi(gq.z)) * acc[m2][2 * g + 1][1];
;                         tot[m2][2 * g + 1][2] += sigm(bflo(gq.w)) * acc[m2][2 * g + 1][2]; tot[m2][2 * g + 1][3] += sigm(bfhi(gq.w)) * acc[m2][2 * g + 1][3];
;                         acc[m2][2 * g] = ZERO4; acc[m2][2 * g + 1] = ZERO4; }
	v_lshlrev_b32_e32 v54, 16, v55
	v_and_b32_e32 v55, 0xffff0000, v55
	v_mul_f32_e32 v55, 0xbfb8aa3b, v55
	v_exp_f32_e32 v55, v55
	v_mul_f32_e32 v54, 0xbfb8aa3b, v54
	v_exp_f32_e32 v54, v54
	v_fma_f32 v53, v53, v56, v162
	v_add_f32_e32 v55, 1.0, v55
	v_rcp_f32_e32 v55, v55
	v_add_f32_e32 v54, 1.0, v54
	v_rcp_f32_e32 v54, v54
	v_fmac_f32_e32 v165, v55, v59
	v_lshlrev_b32_e32 v55, 16, v44
	v_and_b32_e32 v44, 0xffff0000, v44
	v_mul_f32_e32 v44, 0xbfb8aa3b, v44
	v_exp_f32_e32 v44, v44
	v_mul_f32_e32 v55, 0xbfb8aa3b, v55
	v_exp_f32_e32 v55, v55
	v_fma_f32 v54, v54, v58, v164
	v_add_f32_e32 v44, 1.0, v44
	v_rcp_f32_e32 v44, v44
	v_add_f32_e32 v55, 1.0, v55
	v_rcp_f32_e32 v55, v55
	v_fmac_f32_e32 v159, v49, v44
	v_lshlrev_b32_e32 v44, 16, v45
	v_and_b32_e32 v45, 0xffff0000, v45
	v_mul_f32_e32 v45, 0xbfb8aa3b, v45
	v_exp_f32_e32 v45, v45
	v_mul_f32_e32 v44, 0xbfb8aa3b, v44
	v_exp_f32_e32 v44, v44
	v_fma_f32 v48, v48, v55, v158
	v_add_f32_e32 v45, 1.0, v45
	v_rcp_f32_e32 v45, v45
	v_add_f32_e32 v44, 1.0, v44
	v_rcp_f32_e32 v44, v44
	v_fmac_f32_e32 v161, v51, v45
	v_lshlrev_b32_e32 v45, 16, v46
	v_mul_f32_e32 v45, 0xbfb8aa3b, v45
	v_exp_f32_e32 v45, v45
	v_fma_f32 v44, v50, v44, v160
	v_add_f32_e32 v45, 1.0, v45
	v_rcp_f32_e32 v45, v45
	s_nop 0
	v_fma_f32 v40, v40, v45, v154
	v_and_b32_e32 v45, 0xffff0000, v46
	v_mul_f32_e32 v45, 0xbfb8aa3b, v45
	v_exp_f32_e32 v45, v45
	s_nop 0
	v_add_f32_e32 v45, 1.0, v45
	v_rcp_f32_e32 v45, v45
	s_nop 0
	v_fmac_f32_e32 v155, v41, v45
	v_lshlrev_b32_e32 v41, 16, v47
	v_mul_f32_e32 v41, 0xbfb8aa3b, v41
	v_exp_f32_e32 v41, v41
	s_nop 0
	v_add_f32_e32 v41, 1.0, v41
	v_rcp_f32_e32 v41, v41
	s_nop 0
	v_fma_f32 v41, v42, v41, v156
	v_and_b32_e32 v42, 0xffff0000, v47
	v_mul_f32_e32 v42, 0xbfb8aa3b, v42
	v_exp_f32_e32 v42, v42
	s_nop 0
	v_add_f32_e32 v42, 1.0, v42
	v_rcp_f32_e32 v42, v42
	s_nop 0
	v_fmac_f32_e32 v157, v43, v42
	v_lshlrev_b32_e32 v42, 16, v32
	v_and_b32_e32 v32, 0xffff0000, v32
	v_mul_f32_e32 v32, 0xbfb8aa3b, v32
	v_exp_f32_e32 v32, v32
	v_mul_f32_e32 v42, 0xbfb8aa3b, v42
	v_exp_f32_e32 v42, v42
	v_add_f32_e32 v32, 1.0, v32
	v_rcp_f32_e32 v32, v32
	v_add_f32_e32 v42, 1.0, v42
	v_rcp_f32_e32 v42, v42
	v_fmac_f32_e32 v151, v37, v32
	v_lshlrev_b32_e32 v32, 16, v33
	v_and_b32_e32 v33, 0xffff0000, v33
	v_mul_f32_e32 v33, 0xbfb8aa3b, v33
	v_exp_f32_e32 v33, v33
	v_mul_f32_e32 v32, 0xbfb8aa3b, v32
	v_exp_f32_e32 v32, v32
	v_fma_f32 v36, v36, v42, v150
	v_add_f32_e32 v33, 1.0, v33
	v_rcp_f32_e32 v33, v33
	v_add_f32_e32 v32, 1.0, v32
	v_rcp_f32_e32 v32, v32
	v_fmac_f32_e32 v153, v39, v33
	v_lshlrev_b32_e32 v33, 16, v34
	v_mul_f32_e32 v33, 0xbfb8aa3b, v33
	v_exp_f32_e32 v33, v33
	v_fma_f32 v32, v38, v32, v152
	v_add_f32_e32 v33, 1.0, v33
	v_rcp_f32_e32 v33, v33
	s_nop 0
	v_fma_f32 v28, v28, v33, v146
	v_and_b32_e32 v33, 0xffff0000, v34
	v_mul_f32_e32 v33, 0xbfb8aa3b, v33
	v_exp_f32_e32 v33, v33
	s_nop 0
	v_add_f32_e32 v33, 1.0, v33
	v_rcp_f32_e32 v33, v33
	s_nop 0
	v_fmac_f32_e32 v147, v29, v33
	v_lshlrev_b32_e32 v29, 16, v35
	v_mul_f32_e32 v29, 0xbfb8aa3b, v29
	v_exp_f32_e32 v29, v29
	s_nop 0
	v_add_f32_e32 v29, 1.0, v29
	v_rcp_f32_e32 v29, v29
	s_nop 0
	v_fma_f32 v29, v30, v29, v148
	v_and_b32_e32 v30, 0xffff0000, v35
	v_mul_f32_e32 v30, 0xbfb8aa3b, v30
	v_exp_f32_e32 v30, v30
	s_nop 0
	v_add_f32_e32 v30, 1.0, v30
	v_rcp_f32_e32 v30, v30
	s_nop 0
	v_fmac_f32_e32 v149, v31, v30
	s_waitcnt vmcnt(1)
	v_lshlrev_b32_e32 v30, 16, v20
	v_and_b32_e32 v20, 0xffff0000, v20
	v_mul_f32_e32 v20, 0xbfb8aa3b, v20
	v_exp_f32_e32 v20, v20
	v_mul_f32_e32 v30, 0xbfb8aa3b, v30
	v_exp_f32_e32 v30, v30
	v_add_f32_e32 v20, 1.0, v20
	v_rcp_f32_e32 v20, v20
	v_add_f32_e32 v30, 1.0, v30
	v_rcp_f32_e32 v30, v30
	v_fmac_f32_e32 v129, v25, v20
	v_lshlrev_b32_e32 v20, 16, v21
	v_and_b32_e32 v21, 0xffff0000, v21
	v_mul_f32_e32 v21, 0xbfb8aa3b, v21
	v_exp_f32_e32 v21, v21
	v_mul_f32_e32 v20, 0xbfb8aa3b, v20
	v_exp_f32_e32 v20, v20
	v_fma_f32 v24, v24, v30, v128
	v_add_f32_e32 v21, 1.0, v21
	v_rcp_f32_e32 v21, v21
	v_add_f32_e32 v20, 1.0, v20
	v_rcp_f32_e32 v20, v20
	v_fmac_f32_e32 v131, v27, v21
	v_lshlrev_b32_e32 v21, 16, v22
	v_mul_f32_e32 v21, 0xbfb8aa3b, v21
	v_exp_f32_e32 v21, v21
	v_fma_f32 v20, v26, v20, v130
	v_add_f32_e32 v21, 1.0, v21
	v_rcp_f32_e32 v21, v21
	s_nop 0
	v_fma_f32 v16, v16, v21, v124
	v_and_b32_e32 v21, 0xffff0000, v22
	v_mul_f32_e32 v21, 0xbfb8aa3b, v21
	v_exp_f32_e32 v21, v21
	s_nop 0
	v_add_f32_e32 v21, 1.0, v21
	v_rcp_f32_e32 v21, v21
	s_nop 0
	v_fmac_f32_e32 v125, v17, v21
	v_lshlrev_b32_e32 v17, 16, v23
	v_mul_f32_e32 v17, 0xbfb8aa3b, v17
	v_exp_f32_e32 v17, v17
	s_nop 0
	v_add_f32_e32 v17, 1.0, v17
	v_rcp_f32_e32 v17, v17
	s_nop 0
	v_fma_f32 v17, v18, v17, v126
	v_and_b32_e32 v18, 0xffff0000, v23
	v_mul_f32_e32 v18, 0xbfb8aa3b, v18
	v_exp_f32_e32 v18, v18
	s_nop 0
	v_add_f32_e32 v18, 1.0, v18
	v_rcp_f32_e32 v18, v18
	s_nop 0
	v_fmac_f32_e32 v127, v19, v18
	s_waitcnt vmcnt(0)
; __device__ __forceinline__ unsigned pk2(float lo, float hi) { unsigned r; asm("v_cvt_pk_bf16_f32 %0, %1, %2" : "=v"(r) : "v"(lo), "v"(hi)); return r; }
; #define BG_BAR() do { __builtin_amdgcn_s_barrier(); asm volatile("" ::: "memory"); } while (0)
; __device__ __forceinline__ void bgemm_phase(LAS unsigned char* lds, const bf16_t* outs, const bf16_t* wbr, const bf16_t* zg, bf16_t* merged) {
;     ...
; #pragma unroll
;         for (int mi = 0; mi < 4; ++mi) { size_t ooff = (size_t)(pm * 256 + wm * 64 + mi * 16 + fr) * D + pn * 128 + wn * 64 + fq * 8; asm volatile("" : "+v"(ooff)); bf16_t* op = merged + ooff;
; #pragma unroll
;             for (int g = 0; g < 2; ++g) { u32x4 w; w.x = pk2(tot[mi][2 * g][0], tot[mi][2 * g][1]); w.y = pk2(tot[mi][2 * g][2], tot[mi][2 * g][3]);
;                 w.z = pk2(tot[mi][2 * g + 1][0], tot[mi][2 * g + 1][1]); w.w = pk2(tot[mi][2 * g + 1][2], tot[mi][2 * g + 1][3]); *(u32x4*)(op + g * 32) = w; } }
;         BG_BAR();
;     }
;     asm volatile("s_waitcnt vmcnt(0)" ::: "memory"); __syncthreads();
	v_lshlrev_b32_e32 v18, 16, v8
	v_and_b32_e32 v8, 0xffff0000, v8
	v_mul_f32_e32 v8, 0xbfb8aa3b, v8
	v_exp_f32_e32 v8, v8
	v_mul_f32_e32 v18, 0xbfb8aa3b, v18
	v_exp_f32_e32 v18, v18
	v_add_f32_e32 v8, 1.0, v8
	v_rcp_f32_e32 v8, v8
	v_add_f32_e32 v18, 1.0, v18
	v_rcp_f32_e32 v18, v18
	v_fmac_f32_e32 v121, v13, v8
	v_lshlrev_b32_e32 v8, 16, v9
	v_mul_f32_e32 v8, 0xbfb8aa3b, v8
	v_exp_f32_e32 v8, v8
	v_fma_f32 v12, v12, v18, v120
	v_lshl_or_b32 v18, s36, 7, v216
	v_add_f32_e32 v8, 1.0, v8
	v_rcp_f32_e32 v8, v8
	s_nop 0
	v_fma_f32 v13, v14, v8, v122
	v_and_b32_e32 v8, 0xffff0000, v9
	v_mul_f32_e32 v8, 0xbfb8aa3b, v8
	v_exp_f32_e32 v8, v8
	s_nop 0
	v_add_f32_e32 v8, 1.0, v8
	v_rcp_f32_e32 v8, v8
	s_nop 0
	v_fmac_f32_e32 v123, v15, v8
	v_lshlrev_b32_e32 v8, 16, v10
	v_mul_f32_e32 v8, 0xbfb8aa3b, v8
	v_exp_f32_e32 v8, v8
	s_nop 0
	v_add_f32_e32 v8, 1.0, v8
	v_rcp_f32_e32 v8, v8
	s_nop 0
	v_fma_f32 v14, v4, v8, v116
	v_and_b32_e32 v4, 0xffff0000, v10
	v_mul_f32_e32 v4, 0xbfb8aa3b, v4
	v_exp_f32_e32 v4, v4
	v_lshl_add_u32 v8, s35, 5, v215
	v_ashrrev_i32_e32 v9, 31, v8
	v_add_f32_e32 v4, 1.0, v4
	v_rcp_f32_e32 v4, v4
	s_nop 0
	v_fmac_f32_e32 v117, v5, v4
	v_lshlrev_b32_e32 v4, 16, v11
	v_mul_f32_e32 v4, 0xbfb8aa3b, v4
	v_exp_f32_e32 v4, v4
	s_nop 0
	v_add_f32_e32 v4, 1.0, v4
	v_rcp_f32_e32 v4, v4
	s_nop 0
	v_fma_f32 v15, v6, v4, v118
	v_and_b32_e32 v4, 0xffff0000, v11
	v_mul_f32_e32 v4, 0xbfb8aa3b, v4
	v_exp_f32_e32 v4, v4
	v_cvt_pk_bf16_f32 v6, v89, v187
	s_nop 0
	v_add_f32_e32 v4, 1.0, v4
	v_rcp_f32_e32 v4, v4
	s_nop 0
	v_fmac_f32_e32 v119, v7, v4
	v_lshlrev_b64 v[4:5], 10, v[8:9]
	v_or_b32_e32 v4, v4, v18
	v_cvt_pk_bf16_f32 v7, v90, v189
	s_nop 0
	v_lshl_add_u64 v[10:11], v[4:5], 1, s[4:5]
	v_cvt_pk_bf16_f32 v4, v96, v191
	v_cvt_pk_bf16_f32 v5, v88, v193
	global_store_dwordx4 v[10:11], v[4:7], off
	s_nop 1
	v_cvt_pk_bf16_f32 v4, v84, v183
	v_cvt_pk_bf16_f32 v5, v76, v185
	v_cvt_pk_bf16_f32 v6, v77, v179
	v_cvt_pk_bf16_f32 v7, v78, v181
	global_store_dwordx4 v[10:11], v[4:7], off offset:64
	s_nop 1
	v_or_b32_e32 v4, 16, v8
	v_ashrrev_i32_e32 v5, 31, v4
	v_lshlrev_b64 v[4:5], 10, v[4:5]
	v_or_b32_e32 v4, v4, v18
	v_cvt_pk_bf16_f32 v6, v65, v171
	v_cvt_pk_bf16_f32 v7, v66, v173
	s_nop 0
	v_lshl_add_u64 v[10:11], v[4:5], 1, s[4:5]
	v_cvt_pk_bf16_f32 v4, v72, v175
	v_cvt_pk_bf16_f32 v5, v64, v177
	global_store_dwordx4 v[10:11], v[4:7], off
	s_nop 1
	v_cvt_pk_bf16_f32 v4, v60, v167
	v_cvt_pk_bf16_f32 v5, v52, v169
	v_cvt_pk_bf16_f32 v6, v53, v163
	v_cvt_pk_bf16_f32 v7, v54, v165
	global_store_dwordx4 v[10:11], v[4:7], off offset:64
	s_nop 1
	v_or_b32_e32 v4, 32, v8
	v_ashrrev_i32_e32 v5, 31, v4
	v_lshlrev_b64 v[4:5], 10, v[4:5]
	v_or_b32_e32 v4, v4, v18
	v_cvt_pk_bf16_f32 v6, v40, v155
	v_cvt_pk_bf16_f32 v7, v41, v157
	s_nop 0
	v_lshl_add_u64 v[10:11], v[4:5], 1, s[4:5]
	v_cvt_pk_bf16_f32 v4, v48, v159
	v_cvt_pk_bf16_f32 v5, v44, v161
	global_store_dwordx4 v[10:11], v[4:7], off
	s_nop 1
	v_cvt_pk_bf16_f32 v4, v36, v151
	v_cvt_pk_bf16_f32 v5, v32, v153
	v_cvt_pk_bf16_f32 v6, v28, v147
	v_cvt_pk_bf16_f32 v7, v29, v149
	global_store_dwordx4 v[10:11], v[4:7], off offset:64
	s_nop 1
	v_or_b32_e32 v4, 48, v8
	v_ashrrev_i32_e32 v5, 31, v4
	v_lshlrev_b64 v[4:5], 10, v[4:5]
	v_or_b32_e32 v4, v4, v18
	v_cvt_pk_bf16_f32 v6, v16, v125
	v_cvt_pk_bf16_f32 v7, v17, v127
	s_nop 0
	v_lshl_add_u64 v[8:9], v[4:5], 1, s[4:5]
	v_cvt_pk_bf16_f32 v4, v24, v129
	v_cvt_pk_bf16_f32 v5, v20, v131
	global_store_dwordx4 v[8:9], v[4:7], off
	s_nop 1
	v_cvt_pk_bf16_f32 v4, v12, v121
	v_cvt_pk_bf16_f32 v5, v13, v123
	v_cvt_pk_bf16_f32 v6, v14, v117
	v_cvt_pk_bf16_f32 v7, v15, v119
	global_store_dwordx4 v[8:9], v[4:7], off offset:64
	s_barrier
	s_add_i32 s0, s12, s0
	s_cmpk_gt_i32 s0, 0x1ff
	s_cbranch_scc0 .LBB0_295
.LBB0_298:
	v_mov_b32_e32 v136, 0x100
	v_mov_b32_e32 v137, 0
	v_mov_b32_e32 v138, 0xff
	v_mov_b32_e32 v139, 0
	v_mov_b32_e32 v204, 0x358637bd
	v_mov_b32_e32 v205, 0x260
	v_mov_b32_e32 v206, 0x3ecc95a3
	v_mbcnt_lo_u32_b32 v207, -1, 0
	v_mbcnt_hi_u32_b32 v207, -1, v207
	v_mov_b32_e32 v208, 0x6bf
	v_mov_b32_e32 v209, 0
	v_mov_b32_e32 v210, 0xb00000
	v_mov_b32_e32 v211, 0x41b17218
	s_waitcnt vmcnt(0)
	s_mov_b32 s38, 0x16000
	v_mov_b64_e32 v[238:239], 0x57f
	v_mov_b64_e32 v[240:241], 0x580
	v_mov_b32_e32 v243, v212
	v_mov_b32_e32 v212, v210
	v_mov_b32_e32 v210, 0x1600
	v_mov_b64_e32 v[244:245], 0x6c0
	s_barrier
